# PLE epilogues (phases 14, 27): X and E residual loads hoisted in a rolling 8-step window with counted vmcnt
# baseline (speedup 1.0000x reference)
.LBB0_1244:
	v_lshl_add_u32 v148, s46, 8, v150
	v_lshl_or_b32 v146, s33, 8, v152
	v_ashrrev_i32_e32 v149, 31, v148
	v_ashrrev_i32_e32 v147, 31, v146
	v_lshlrev_b64 v[144:145], 11, v[148:149]
	v_lshl_add_u64 v[144:145], v[144:145], 0, v[146:147]
	v_lshlrev_b64 v[144:145], 1, v[144:145]
	v_lshl_add_u64 v[156:157], s[10:11], 0, v[144:145]
	v_lshl_add_u64 v[160:161], s[12:13], 0, v[144:145]
	v_mov_b32_e32 v246, v156
	v_mov_b32_e32 v247, v157
	v_mov_b32_e32 v248, v160
	v_mov_b32_e32 v249, v161
	global_load_dwordx4 v[180:183], v[246:247], off
	global_load_dwordx4 v[184:187], v[248:249], off
	global_load_dwordx4 v[188:191], v[246:247], off offset:256
	global_load_dwordx4 v[192:195], v[248:249], off offset:256
	s_mov_b64 s[98:99], 0x10000
	v_lshl_add_u64 v[250:251], v[246:247], 0, s[98:99]
	global_load_dwordx4 v[196:199], v[250:251], off
	v_lshl_add_u64 v[252:253], v[248:249], 0, s[98:99]
	global_load_dwordx4 v[200:203], v[252:253], off
	s_mov_b64 s[98:99], 0x10000
	v_lshl_add_u64 v[250:251], v[246:247], 0, s[98:99]
	global_load_dwordx4 v[204:207], v[250:251], off offset:256
	v_lshl_add_u64 v[252:253], v[248:249], 0, s[98:99]
	global_load_dwordx4 v[208:211], v[252:253], off offset:256
	s_mov_b64 s[98:99], 0x20000
	v_lshl_add_u64 v[250:251], v[246:247], 0, s[98:99]
	global_load_dwordx4 v[214:217], v[250:251], off
	v_lshl_add_u64 v[252:253], v[248:249], 0, s[98:99]
	global_load_dwordx4 v[218:221], v[252:253], off
	s_mov_b64 s[98:99], 0x20000
	v_lshl_add_u64 v[250:251], v[246:247], 0, s[98:99]
	global_load_dwordx4 v[222:225], v[250:251], off offset:256
	v_lshl_add_u64 v[252:253], v[248:249], 0, s[98:99]
	global_load_dwordx4 v[226:229], v[252:253], off offset:256
	s_mov_b64 s[98:99], 0x30000
	v_lshl_add_u64 v[250:251], v[246:247], 0, s[98:99]
	global_load_dwordx4 v[230:233], v[250:251], off
	v_lshl_add_u64 v[252:253], v[248:249], 0, s[98:99]
	global_load_dwordx4 v[234:237], v[252:253], off
	s_mov_b64 s[98:99], 0x30000
	v_lshl_add_u64 v[250:251], v[246:247], 0, s[98:99]
	global_load_dwordx4 v[238:241], v[250:251], off offset:256
	v_lshl_add_u64 v[252:253], v[248:249], 0, s[98:99]
	global_load_dwordx4 v[242:245], v[252:253], off offset:256
	s_nop 1
	s_waitcnt vmcnt(14)
	v_mov_b32_e32 v156, v180
	v_mov_b32_e32 v157, v181
	v_mov_b32_e32 v158, v182
	v_mov_b32_e32 v159, v183
	v_mul_f32_e32 v124, 0xbfb8aa3b, v124
	s_nop 1
	v_mov_b32_e32 v160, v184
	v_mov_b32_e32 v161, v185
	v_mov_b32_e32 v162, v186
	v_mov_b32_e32 v163, v187
	s_mov_b64 s[98:99], 0x80000
	v_lshl_add_u64 v[250:251], v[246:247], 0, s[98:99]
	global_load_dwordx4 v[180:183], v[250:251], off
	v_lshl_add_u64 v[252:253], v[248:249], 0, s[98:99]
	global_load_dwordx4 v[184:187], v[252:253], off
	v_mul_f32_e32 v125, 0xbfb8aa3b, v125
	v_mul_f32_e32 v126, 0xbfb8aa3b, v126
	v_mul_f32_e32 v127, 0xbfb8aa3b, v127
	v_mul_f32_e32 v120, 0xbfb8aa3b, v120
	v_mul_f32_e32 v121, 0xbfb8aa3b, v121
	v_mul_f32_e32 v122, 0xbfb8aa3b, v122
	v_mul_f32_e32 v123, 0xbfb8aa3b, v123
	v_exp_f32_e32 v124, v124
	v_exp_f32_e32 v125, v125
	v_exp_f32_e32 v126, v126
	v_exp_f32_e32 v127, v127
	v_exp_f32_e32 v120, v120
	v_exp_f32_e32 v121, v121
	v_exp_f32_e32 v122, v122
	v_exp_f32_e32 v123, v123
	v_add_f32_e32 v149, 1.0, v124
	v_add_f32_e32 v166, 1.0, v125
	v_add_f32_e32 v126, 1.0, v126
	v_add_f32_e32 v127, 1.0, v127
	v_add_f32_e32 v120, 1.0, v120
	v_add_f32_e32 v121, 1.0, v121
	v_add_f32_e32 v122, 1.0, v122
	v_add_f32_e32 v123, 1.0, v123
	v_rcp_f32_e32 v149, v149
	v_rcp_f32_e32 v168, v166
	v_rcp_f32_e32 v169, v126
	v_rcp_f32_e32 v170, v127
	v_rcp_f32_e32 v120, v120
	v_rcp_f32_e32 v121, v121
	v_rcp_f32_e32 v122, v122
	v_rcp_f32_e32 v123, v123
	v_lshl_add_u64 v[124:125], s[14:15], 0, v[144:145]
	v_or_b32_e32 v164, 0x100, v144
	v_mov_b32_e32 v165, v145
	v_lshl_add_u64 v[126:127], s[10:11], 0, v[164:165]
	v_lshl_add_u64 v[166:167], s[12:13], 0, v[164:165]
	v_mul_f32_e32 v116, 0xbfb8aa3b, v116
	v_mul_f32_e32 v117, 0xbfb8aa3b, v117
	v_mul_f32_e32 v118, 0xbfb8aa3b, v118
	v_mul_f32_e32 v119, 0xbfb8aa3b, v119
	v_mul_f32_e32 v112, 0xbfb8aa3b, v112
	v_mul_f32_e32 v113, 0xbfb8aa3b, v113
	v_mul_f32_e32 v114, 0xbfb8aa3b, v114
	v_mul_f32_e32 v115, 0xbfb8aa3b, v115
	v_exp_f32_e32 v116, v116
	v_exp_f32_e32 v117, v117
	v_exp_f32_e32 v118, v118
	v_exp_f32_e32 v119, v119
	v_exp_f32_e32 v114, v114
	v_exp_f32_e32 v115, v115
	v_add_f32_e32 v116, 1.0, v116
	v_add_f32_e32 v117, 1.0, v117
	v_add_f32_e32 v118, 1.0, v118
	v_add_f32_e32 v119, 1.0, v119
	v_add_f32_e32 v114, 1.0, v114
	v_add_f32_e32 v115, 1.0, v115
	v_rcp_f32_e32 v116, v116
	v_rcp_f32_e32 v117, v117
	v_rcp_f32_e32 v114, v114
	v_rcp_f32_e32 v115, v115
	v_mul_f32_e32 v108, 0xbfb8aa3b, v108
	v_mul_f32_e32 v109, 0xbfb8aa3b, v109
	v_mul_f32_e32 v110, 0xbfb8aa3b, v110
	v_mul_f32_e32 v111, 0xbfb8aa3b, v111
	v_mul_f32_e32 v104, 0xbfb8aa3b, v104
	v_mul_f32_e32 v105, 0xbfb8aa3b, v105
	v_mul_f32_e32 v106, 0xbfb8aa3b, v106
	v_mul_f32_e32 v107, 0xbfb8aa3b, v107
	v_exp_f32_e32 v108, v108
	v_exp_f32_e32 v109, v109
	v_exp_f32_e32 v110, v110
	v_exp_f32_e32 v111, v111
	v_exp_f32_e32 v104, v104
	v_exp_f32_e32 v105, v105
	v_exp_f32_e32 v106, v106
	v_exp_f32_e32 v107, v107
	v_add_f32_e32 v108, 1.0, v108
	v_lshlrev_b32_e32 v171, 16, v156
	v_and_b32_e32 v156, 0xffff0000, v156
	v_lshlrev_b32_e32 v172, 16, v160
	v_and_b32_e32 v160, 0xffff0000, v160
	v_lshlrev_b32_e32 v173, 16, v157
	v_lshlrev_b32_e32 v174, 16, v161
	v_and_b32_e32 v157, 0xffff0000, v157
	v_and_b32_e32 v161, 0xffff0000, v161
	v_lshlrev_b32_e32 v175, 16, v158
	v_lshlrev_b32_e32 v176, 16, v162
	v_and_b32_e32 v158, 0xffff0000, v158
	v_and_b32_e32 v162, 0xffff0000, v162
	v_lshlrev_b32_e32 v177, 16, v159
	v_lshlrev_b32_e32 v178, 16, v163
	v_and_b32_e32 v159, 0xffff0000, v159
	v_and_b32_e32 v163, 0xffff0000, v163
	v_fmac_f32_e32 v171, v149, v172
	v_fmac_f32_e32 v156, v168, v160
	v_fmac_f32_e32 v173, v169, v174
	v_fmac_f32_e32 v157, v170, v161
	v_fmac_f32_e32 v175, v120, v176
	v_fmac_f32_e32 v158, v121, v162
	v_fmac_f32_e32 v177, v122, v178
	v_fmac_f32_e32 v159, v123, v163
	v_cvt_pk_bf16_f32 v120, v171, v156
	v_cvt_pk_bf16_f32 v121, v173, v157
	v_cvt_pk_bf16_f32 v122, v175, v158
	v_cvt_pk_bf16_f32 v123, v177, v159
	global_store_dwordx4 v[124:125], v[120:123], off
	s_nop 1
	s_waitcnt vmcnt(15)
	v_mov_b32_e32 v120, v188
	v_mov_b32_e32 v121, v189
	v_mov_b32_e32 v122, v190
	v_mov_b32_e32 v123, v191
	s_nop 0
	s_nop 1
	v_mov_b32_e32 v124, v192
	v_mov_b32_e32 v125, v193
	v_mov_b32_e32 v126, v194
	v_mov_b32_e32 v127, v195
	s_mov_b64 s[98:99], 0x80000
	v_lshl_add_u64 v[250:251], v[246:247], 0, s[98:99]
	global_load_dwordx4 v[188:191], v[250:251], off offset:256
	v_lshl_add_u64 v[252:253], v[248:249], 0, s[98:99]
	global_load_dwordx4 v[192:195], v[252:253], off offset:256
	v_exp_f32_e32 v149, v112
	v_exp_f32_e32 v156, v113
	v_or_b32_e32 v112, 16, v148
	v_ashrrev_i32_e32 v113, 31, v112
	v_add_f32_e32 v149, 1.0, v149
	v_add_f32_e32 v156, 1.0, v156
	v_rcp_f32_e32 v160, v118
	v_rcp_f32_e32 v161, v119
	v_rcp_f32_e32 v149, v149
	v_rcp_f32_e32 v162, v156
	v_lshlrev_b64 v[112:113], 11, v[112:113]
	v_lshl_add_u64 v[112:113], v[112:113], 0, v[146:147]
	v_lshlrev_b64 v[112:113], 1, v[112:113]
	v_lshl_add_u64 v[118:119], s[14:15], 0, v[164:165]
	v_lshl_add_u64 v[156:157], s[10:11], 0, v[112:113]
	v_lshl_add_u64 v[158:159], s[12:13], 0, v[112:113]
	v_add_f32_e32 v109, 1.0, v109
	v_add_f32_e32 v110, 1.0, v110
	v_add_f32_e32 v111, 1.0, v111
	v_add_f32_e32 v104, 1.0, v104
	v_add_f32_e32 v105, 1.0, v105
	v_add_f32_e32 v106, 1.0, v106
	v_add_f32_e32 v107, 1.0, v107
	v_rcp_f32_e32 v104, v104
	v_rcp_f32_e32 v105, v105
	v_rcp_f32_e32 v106, v106
	v_rcp_f32_e32 v107, v107
	v_mul_f32_e32 v100, 0xbfb8aa3b, v100
	v_mul_f32_e32 v101, 0xbfb8aa3b, v101
	v_mul_f32_e32 v102, 0xbfb8aa3b, v102
	v_mul_f32_e32 v103, 0xbfb8aa3b, v103
	v_mul_f32_e32 v96, 0xbfb8aa3b, v96
	v_mul_f32_e32 v97, 0xbfb8aa3b, v97
	v_mul_f32_e32 v98, 0xbfb8aa3b, v98
	v_mul_f32_e32 v99, 0xbfb8aa3b, v99
	v_exp_f32_e32 v100, v100
	v_exp_f32_e32 v101, v101
	v_exp_f32_e32 v102, v102
	v_exp_f32_e32 v103, v103
	v_exp_f32_e32 v98, v98
	v_exp_f32_e32 v99, v99
	v_add_f32_e32 v100, 1.0, v100
	v_add_f32_e32 v101, 1.0, v101
	v_add_f32_e32 v102, 1.0, v102
	v_add_f32_e32 v103, 1.0, v103
	v_add_f32_e32 v98, 1.0, v98
	v_add_f32_e32 v99, 1.0, v99
	v_rcp_f32_e32 v100, v100
	v_rcp_f32_e32 v101, v101
	v_rcp_f32_e32 v98, v98
	v_rcp_f32_e32 v99, v99
	v_mul_f32_e32 v92, 0xbfb8aa3b, v92
	v_mul_f32_e32 v93, 0xbfb8aa3b, v93
	v_mul_f32_e32 v94, 0xbfb8aa3b, v94
	v_mul_f32_e32 v95, 0xbfb8aa3b, v95
	v_mul_f32_e32 v88, 0xbfb8aa3b, v88
	v_mul_f32_e32 v89, 0xbfb8aa3b, v89
	v_mul_f32_e32 v90, 0xbfb8aa3b, v90
	v_mul_f32_e32 v91, 0xbfb8aa3b, v91
	v_exp_f32_e32 v92, v92
	v_exp_f32_e32 v93, v93
	v_exp_f32_e32 v94, v94
	v_exp_f32_e32 v95, v95
	v_exp_f32_e32 v88, v88
	v_exp_f32_e32 v89, v89
	v_exp_f32_e32 v90, v90
	v_exp_f32_e32 v91, v91
	v_add_f32_e32 v92, 1.0, v92
	v_add_f32_e32 v93, 1.0, v93
	v_add_f32_e32 v94, 1.0, v94
	v_add_f32_e32 v95, 1.0, v95
	v_add_f32_e32 v88, 1.0, v88
	v_add_f32_e32 v89, 1.0, v89
	v_add_f32_e32 v90, 1.0, v90
	v_add_f32_e32 v91, 1.0, v91
	v_rcp_f32_e32 v88, v88
	v_rcp_f32_e32 v89, v89
	v_rcp_f32_e32 v90, v90
	v_lshlrev_b32_e32 v163, 16, v120
	v_lshlrev_b32_e32 v164, 16, v124
	v_and_b32_e32 v120, 0xffff0000, v120
	v_and_b32_e32 v124, 0xffff0000, v124
	v_lshlrev_b32_e32 v165, 16, v121
	v_lshlrev_b32_e32 v166, 16, v125
	v_and_b32_e32 v121, 0xffff0000, v121
	v_and_b32_e32 v125, 0xffff0000, v125
	v_lshlrev_b32_e32 v167, 16, v122
	v_lshlrev_b32_e32 v168, 16, v126
	v_and_b32_e32 v122, 0xffff0000, v122
	v_and_b32_e32 v126, 0xffff0000, v126
	v_lshlrev_b32_e32 v169, 16, v123
	v_lshlrev_b32_e32 v170, 16, v127
	v_and_b32_e32 v123, 0xffff0000, v123
	v_and_b32_e32 v127, 0xffff0000, v127
	v_fmac_f32_e32 v163, v116, v164
	v_fmac_f32_e32 v120, v117, v124
	v_fmac_f32_e32 v165, v160, v166
	v_fmac_f32_e32 v121, v161, v125
	v_fmac_f32_e32 v167, v149, v168
	v_fmac_f32_e32 v122, v162, v126
	v_fmac_f32_e32 v169, v114, v170
	v_fmac_f32_e32 v123, v115, v127
	v_cvt_pk_bf16_f32 v114, v163, v120
	v_cvt_pk_bf16_f32 v115, v165, v121
	v_cvt_pk_bf16_f32 v116, v167, v122
	v_cvt_pk_bf16_f32 v117, v169, v123
	global_store_dwordx4 v[118:119], v[114:117], off
	s_nop 1
	s_waitcnt vmcnt(16)
	v_mov_b32_e32 v114, v196
	v_mov_b32_e32 v115, v197
	v_mov_b32_e32 v116, v198
	v_mov_b32_e32 v117, v199
	s_nop 0
	s_nop 1
	v_mov_b32_e32 v118, v200
	v_mov_b32_e32 v119, v201
	v_mov_b32_e32 v120, v202
	v_mov_b32_e32 v121, v203
	s_mov_b64 s[98:99], 0x90000
	v_lshl_add_u64 v[250:251], v[246:247], 0, s[98:99]
	global_load_dwordx4 v[196:199], v[250:251], off
	v_lshl_add_u64 v[252:253], v[248:249], 0, s[98:99]
	global_load_dwordx4 v[200:203], v[252:253], off
	v_rcp_f32_e32 v124, v108
	v_rcp_f32_e32 v125, v109
	v_rcp_f32_e32 v126, v110
	v_rcp_f32_e32 v127, v111
	v_lshl_add_u64 v[108:109], s[14:15], 0, v[112:113]
	v_or_b32_e32 v112, 0x100, v112
	v_lshl_add_u64 v[110:111], s[10:11], 0, v[112:113]
	v_lshl_add_u64 v[122:123], s[12:13], 0, v[112:113]
	v_lshl_add_u64 v[112:113], s[14:15], 0, v[112:113]
	v_rcp_f32_e32 v91, v91
	v_mul_f32_e32 v84, 0xbfb8aa3b, v84
	v_mul_f32_e32 v85, 0xbfb8aa3b, v85
	v_mul_f32_e32 v86, 0xbfb8aa3b, v86
	v_mul_f32_e32 v87, 0xbfb8aa3b, v87
	v_mul_f32_e32 v80, 0xbfb8aa3b, v80
	v_mul_f32_e32 v81, 0xbfb8aa3b, v81
	v_mul_f32_e32 v82, 0xbfb8aa3b, v82
	v_mul_f32_e32 v83, 0xbfb8aa3b, v83
	v_exp_f32_e32 v84, v84
	v_exp_f32_e32 v85, v85
	v_exp_f32_e32 v86, v86
	v_exp_f32_e32 v87, v87
	v_exp_f32_e32 v82, v82
	v_exp_f32_e32 v83, v83
	v_add_f32_e32 v84, 1.0, v84
	v_add_f32_e32 v85, 1.0, v85
	v_add_f32_e32 v86, 1.0, v86
	v_add_f32_e32 v87, 1.0, v87
	v_add_f32_e32 v82, 1.0, v82
	v_add_f32_e32 v83, 1.0, v83
	v_rcp_f32_e32 v84, v84
	v_rcp_f32_e32 v85, v85
	v_rcp_f32_e32 v82, v82
	v_rcp_f32_e32 v83, v83
	v_mul_f32_e32 v76, 0xbfb8aa3b, v76
	v_mul_f32_e32 v77, 0xbfb8aa3b, v77
	v_mul_f32_e32 v78, 0xbfb8aa3b, v78
	v_mul_f32_e32 v79, 0xbfb8aa3b, v79
	v_mul_f32_e32 v72, 0xbfb8aa3b, v72
	v_mul_f32_e32 v73, 0xbfb8aa3b, v73
	v_mul_f32_e32 v74, 0xbfb8aa3b, v74
	v_mul_f32_e32 v75, 0xbfb8aa3b, v75
	v_exp_f32_e32 v76, v76
	v_exp_f32_e32 v77, v77
	v_exp_f32_e32 v78, v78
	v_exp_f32_e32 v79, v79
	v_exp_f32_e32 v72, v72
	v_exp_f32_e32 v73, v73
	v_exp_f32_e32 v74, v74
	v_exp_f32_e32 v75, v75
	v_add_f32_e32 v76, 1.0, v76
	v_add_f32_e32 v77, 1.0, v77
	v_add_f32_e32 v78, 1.0, v78
	v_add_f32_e32 v79, 1.0, v79
	v_add_f32_e32 v72, 1.0, v72
	v_add_f32_e32 v73, 1.0, v73
	v_add_f32_e32 v74, 1.0, v74
	v_add_f32_e32 v75, 1.0, v75
	v_rcp_f32_e32 v72, v72
	v_rcp_f32_e32 v73, v73
	v_rcp_f32_e32 v74, v74
	v_rcp_f32_e32 v75, v75
	v_mul_f32_e32 v68, 0xbfb8aa3b, v68
	v_mul_f32_e32 v69, 0xbfb8aa3b, v69
	v_mul_f32_e32 v70, 0xbfb8aa3b, v70
	v_mul_f32_e32 v71, 0xbfb8aa3b, v71
	v_mul_f32_e32 v64, 0xbfb8aa3b, v64
	v_mul_f32_e32 v65, 0xbfb8aa3b, v65
	v_mul_f32_e32 v66, 0xbfb8aa3b, v66
	v_mul_f32_e32 v67, 0xbfb8aa3b, v67
	v_exp_f32_e32 v68, v68
	v_exp_f32_e32 v69, v69
	v_exp_f32_e32 v70, v70
	v_exp_f32_e32 v71, v71
	v_exp_f32_e32 v64, v64
	v_exp_f32_e32 v65, v65
	v_exp_f32_e32 v66, v66
	v_exp_f32_e32 v67, v67
	v_lshlrev_b32_e32 v149, 16, v114
	v_lshlrev_b32_e32 v156, 16, v118
	v_and_b32_e32 v114, 0xffff0000, v114
	v_and_b32_e32 v118, 0xffff0000, v118
	v_lshlrev_b32_e32 v157, 16, v115
	v_lshlrev_b32_e32 v158, 16, v119
	v_and_b32_e32 v115, 0xffff0000, v115
	v_and_b32_e32 v119, 0xffff0000, v119
	v_lshlrev_b32_e32 v159, 16, v116
	v_lshlrev_b32_e32 v160, 16, v120
	v_and_b32_e32 v116, 0xffff0000, v116
	v_and_b32_e32 v120, 0xffff0000, v120
	v_lshlrev_b32_e32 v161, 16, v117
	v_lshlrev_b32_e32 v162, 16, v121
	v_and_b32_e32 v117, 0xffff0000, v117
	v_and_b32_e32 v121, 0xffff0000, v121
	v_fmac_f32_e32 v149, v124, v156
	v_fmac_f32_e32 v114, v125, v118
	v_fmac_f32_e32 v157, v126, v158
	v_fmac_f32_e32 v115, v127, v119
	v_fmac_f32_e32 v159, v104, v160
	v_fmac_f32_e32 v116, v105, v120
	v_fmac_f32_e32 v161, v106, v162
	v_fmac_f32_e32 v117, v107, v121
	v_cvt_pk_bf16_f32 v104, v149, v114
	v_cvt_pk_bf16_f32 v105, v157, v115
	v_cvt_pk_bf16_f32 v106, v159, v116
	v_cvt_pk_bf16_f32 v107, v161, v117
	global_store_dwordx4 v[108:109], v[104:107], off
	s_nop 1
	s_waitcnt vmcnt(17)
	v_mov_b32_e32 v104, v204
	v_mov_b32_e32 v105, v205
	v_mov_b32_e32 v106, v206
	v_mov_b32_e32 v107, v207
	s_nop 0
	s_nop 1
	v_mov_b32_e32 v108, v208
	v_mov_b32_e32 v109, v209
	v_mov_b32_e32 v110, v210
	v_mov_b32_e32 v111, v211
	s_mov_b64 s[98:99], 0x90000
	v_lshl_add_u64 v[250:251], v[246:247], 0, s[98:99]
	global_load_dwordx4 v[204:207], v[250:251], off offset:256
	v_lshl_add_u64 v[252:253], v[248:249], 0, s[98:99]
	global_load_dwordx4 v[208:211], v[252:253], off offset:256
	v_exp_f32_e32 v114, v96
	v_exp_f32_e32 v115, v97
	v_or_b32_e32 v96, 32, v148
	v_ashrrev_i32_e32 v97, 31, v96
	v_add_f32_e32 v114, 1.0, v114
	v_add_f32_e32 v115, 1.0, v115
	v_rcp_f32_e32 v116, v102
	v_rcp_f32_e32 v117, v103
	v_rcp_f32_e32 v118, v114
	v_rcp_f32_e32 v119, v115
	v_lshlrev_b64 v[96:97], 11, v[96:97]
	v_lshl_add_u64 v[96:97], v[96:97], 0, v[146:147]
	v_lshlrev_b64 v[96:97], 1, v[96:97]
	v_lshl_add_u64 v[102:103], s[10:11], 0, v[96:97]
	v_lshl_add_u64 v[114:115], s[12:13], 0, v[96:97]
	v_add_f32_e32 v68, 1.0, v68
	v_add_f32_e32 v69, 1.0, v69
	v_add_f32_e32 v70, 1.0, v70
	v_add_f32_e32 v71, 1.0, v71
	v_add_f32_e32 v64, 1.0, v64
	v_add_f32_e32 v65, 1.0, v65
	v_add_f32_e32 v66, 1.0, v66
	v_add_f32_e32 v67, 1.0, v67
	v_rcp_f32_e32 v64, v64
	v_rcp_f32_e32 v65, v65
	v_rcp_f32_e32 v66, v66
	v_rcp_f32_e32 v67, v67
	v_mul_f32_e32 v60, 0xbfb8aa3b, v60
	v_mul_f32_e32 v61, 0xbfb8aa3b, v61
	v_mul_f32_e32 v62, 0xbfb8aa3b, v62
	v_mul_f32_e32 v63, 0xbfb8aa3b, v63
	v_mul_f32_e32 v56, 0xbfb8aa3b, v56
	v_mul_f32_e32 v57, 0xbfb8aa3b, v57
	v_mul_f32_e32 v58, 0xbfb8aa3b, v58
	v_mul_f32_e32 v59, 0xbfb8aa3b, v59
	v_exp_f32_e32 v60, v60
	v_exp_f32_e32 v61, v61
	v_exp_f32_e32 v62, v62
	v_exp_f32_e32 v63, v63
	v_exp_f32_e32 v56, v56
	v_exp_f32_e32 v57, v57
	v_exp_f32_e32 v58, v58
	v_exp_f32_e32 v59, v59
	v_add_f32_e32 v60, 1.0, v60
	v_add_f32_e32 v61, 1.0, v61
	v_add_f32_e32 v62, 1.0, v62
	v_add_f32_e32 v63, 1.0, v63
	v_add_f32_e32 v56, 1.0, v56
	v_add_f32_e32 v57, 1.0, v57
	v_add_f32_e32 v58, 1.0, v58
	v_add_f32_e32 v59, 1.0, v59
	v_rcp_f32_e32 v56, v56
	v_rcp_f32_e32 v57, v57
	v_rcp_f32_e32 v58, v58
	v_rcp_f32_e32 v59, v59
	v_mul_f32_e32 v52, 0xbfb8aa3b, v52
	v_mul_f32_e32 v53, 0xbfb8aa3b, v53
	v_mul_f32_e32 v54, 0xbfb8aa3b, v54
	v_mul_f32_e32 v55, 0xbfb8aa3b, v55
	v_mul_f32_e32 v48, 0xbfb8aa3b, v48
	v_mul_f32_e32 v49, 0xbfb8aa3b, v49
	v_mul_f32_e32 v50, 0xbfb8aa3b, v50
	v_mul_f32_e32 v51, 0xbfb8aa3b, v51
	v_exp_f32_e32 v52, v52
	v_exp_f32_e32 v53, v53
	v_exp_f32_e32 v54, v54
	v_exp_f32_e32 v55, v55
	v_exp_f32_e32 v48, v48
	v_exp_f32_e32 v49, v49
	v_exp_f32_e32 v50, v50
	v_exp_f32_e32 v51, v51
	v_add_f32_e32 v52, 1.0, v52
	v_add_f32_e32 v53, 1.0, v53
	v_add_f32_e32 v54, 1.0, v54
	v_add_f32_e32 v55, 1.0, v55
	v_add_f32_e32 v48, 1.0, v48
	v_add_f32_e32 v49, 1.0, v49
	v_add_f32_e32 v50, 1.0, v50
	v_lshlrev_b32_e32 v120, 16, v104
	v_lshlrev_b32_e32 v121, 16, v108
	v_and_b32_e32 v104, 0xffff0000, v104
	v_and_b32_e32 v108, 0xffff0000, v108
	v_lshlrev_b32_e32 v122, 16, v105
	v_lshlrev_b32_e32 v123, 16, v109
	v_and_b32_e32 v105, 0xffff0000, v105
	v_and_b32_e32 v109, 0xffff0000, v109
	v_lshlrev_b32_e32 v124, 16, v106
	v_lshlrev_b32_e32 v125, 16, v110
	v_and_b32_e32 v106, 0xffff0000, v106
	v_and_b32_e32 v110, 0xffff0000, v110
	v_lshlrev_b32_e32 v126, 16, v107
	v_lshlrev_b32_e32 v127, 16, v111
	v_and_b32_e32 v107, 0xffff0000, v107
	v_and_b32_e32 v111, 0xffff0000, v111
	v_fmac_f32_e32 v120, v100, v121
	v_fmac_f32_e32 v104, v101, v108
	v_fmac_f32_e32 v122, v116, v123
	v_fmac_f32_e32 v105, v117, v109
	v_fmac_f32_e32 v124, v118, v125
	v_fmac_f32_e32 v106, v119, v110
	v_fmac_f32_e32 v126, v98, v127
	v_fmac_f32_e32 v107, v99, v111
	v_cvt_pk_bf16_f32 v98, v120, v104
	v_cvt_pk_bf16_f32 v99, v122, v105
	v_cvt_pk_bf16_f32 v100, v124, v106
	v_cvt_pk_bf16_f32 v101, v126, v107
	global_store_dwordx4 v[112:113], v[98:101], off
	s_nop 1
	s_waitcnt vmcnt(18)
	v_mov_b32_e32 v98, v214
	v_mov_b32_e32 v99, v215
	v_mov_b32_e32 v100, v216
	v_mov_b32_e32 v101, v217
	s_nop 0
	s_nop 1
	v_mov_b32_e32 v102, v218
	v_mov_b32_e32 v103, v219
	v_mov_b32_e32 v104, v220
	v_mov_b32_e32 v105, v221
	s_mov_b64 s[98:99], 0xa0000
	v_lshl_add_u64 v[250:251], v[246:247], 0, s[98:99]
	global_load_dwordx4 v[214:217], v[250:251], off
	v_lshl_add_u64 v[252:253], v[248:249], 0, s[98:99]
	global_load_dwordx4 v[218:221], v[252:253], off
	v_rcp_f32_e32 v108, v92
	v_rcp_f32_e32 v109, v93
	v_rcp_f32_e32 v110, v94
	v_rcp_f32_e32 v111, v95
	v_lshl_add_u64 v[92:93], s[14:15], 0, v[96:97]
	v_or_b32_e32 v96, 0x100, v96
	v_lshl_add_u64 v[94:95], s[10:11], 0, v[96:97]
	v_lshl_add_u64 v[106:107], s[12:13], 0, v[96:97]
	v_lshl_add_u64 v[96:97], s[14:15], 0, v[96:97]
	v_add_f32_e32 v51, 1.0, v51
	v_rcp_f32_e32 v48, v48
	v_rcp_f32_e32 v49, v49
	v_rcp_f32_e32 v50, v50
	v_rcp_f32_e32 v51, v51
	v_mul_f32_e32 v44, 0xbfb8aa3b, v44
	v_mul_f32_e32 v45, 0xbfb8aa3b, v45
	v_mul_f32_e32 v46, 0xbfb8aa3b, v46
	v_mul_f32_e32 v47, 0xbfb8aa3b, v47
	v_mul_f32_e32 v40, 0xbfb8aa3b, v40
	v_mul_f32_e32 v41, 0xbfb8aa3b, v41
	v_mul_f32_e32 v42, 0xbfb8aa3b, v42
	v_mul_f32_e32 v43, 0xbfb8aa3b, v43
	v_exp_f32_e32 v44, v44
	v_exp_f32_e32 v45, v45
	v_exp_f32_e32 v46, v46
	v_exp_f32_e32 v47, v47
	v_exp_f32_e32 v40, v40
	v_exp_f32_e32 v41, v41
	v_exp_f32_e32 v42, v42
	v_exp_f32_e32 v43, v43
	v_add_f32_e32 v44, 1.0, v44
	v_add_f32_e32 v45, 1.0, v45
	v_add_f32_e32 v46, 1.0, v46
	v_add_f32_e32 v47, 1.0, v47
	v_add_f32_e32 v40, 1.0, v40
	v_add_f32_e32 v41, 1.0, v41
	v_add_f32_e32 v42, 1.0, v42
	v_add_f32_e32 v43, 1.0, v43
	v_rcp_f32_e32 v40, v40
	v_rcp_f32_e32 v41, v41
	v_rcp_f32_e32 v42, v42
	v_rcp_f32_e32 v43, v43
	v_mul_f32_e32 v36, 0xbfb8aa3b, v36
	v_mul_f32_e32 v37, 0xbfb8aa3b, v37
	v_mul_f32_e32 v38, 0xbfb8aa3b, v38
	v_mul_f32_e32 v39, 0xbfb8aa3b, v39
	v_mul_f32_e32 v32, 0xbfb8aa3b, v32
	v_mul_f32_e32 v33, 0xbfb8aa3b, v33
	v_mul_f32_e32 v34, 0xbfb8aa3b, v34
	v_mul_f32_e32 v35, 0xbfb8aa3b, v35
	v_exp_f32_e32 v36, v36
	v_exp_f32_e32 v37, v37
	v_exp_f32_e32 v38, v38
	v_exp_f32_e32 v39, v39
	v_exp_f32_e32 v32, v32
	v_exp_f32_e32 v33, v33
	v_exp_f32_e32 v34, v34
	v_exp_f32_e32 v35, v35
	v_add_f32_e32 v36, 1.0, v36
	v_add_f32_e32 v37, 1.0, v37
	v_add_f32_e32 v38, 1.0, v38
	v_add_f32_e32 v39, 1.0, v39
	v_add_f32_e32 v32, 1.0, v32
	v_add_f32_e32 v33, 1.0, v33
	v_add_f32_e32 v34, 1.0, v34
	v_add_f32_e32 v35, 1.0, v35
	v_rcp_f32_e32 v32, v32
	v_rcp_f32_e32 v33, v33
	v_rcp_f32_e32 v34, v34
	v_rcp_f32_e32 v35, v35
	v_mul_f32_e32 v28, 0xbfb8aa3b, v28
	v_mul_f32_e32 v29, 0xbfb8aa3b, v29
	v_mul_f32_e32 v30, 0xbfb8aa3b, v30
	v_mul_f32_e32 v31, 0xbfb8aa3b, v31
	v_mul_f32_e32 v24, 0xbfb8aa3b, v24
	v_mul_f32_e32 v25, 0xbfb8aa3b, v25
	v_mul_f32_e32 v26, 0xbfb8aa3b, v26
	v_mul_f32_e32 v27, 0xbfb8aa3b, v27
	v_lshlrev_b32_e32 v112, 16, v98
	v_lshlrev_b32_e32 v113, 16, v102
	v_and_b32_e32 v98, 0xffff0000, v98
	v_and_b32_e32 v102, 0xffff0000, v102
	v_lshlrev_b32_e32 v114, 16, v99
	v_lshlrev_b32_e32 v115, 16, v103
	v_and_b32_e32 v99, 0xffff0000, v99
	v_and_b32_e32 v103, 0xffff0000, v103
	v_lshlrev_b32_e32 v116, 16, v100
	v_lshlrev_b32_e32 v117, 16, v104
	v_and_b32_e32 v100, 0xffff0000, v100
	v_and_b32_e32 v104, 0xffff0000, v104
	v_lshlrev_b32_e32 v118, 16, v101
	v_lshlrev_b32_e32 v119, 16, v105
	v_and_b32_e32 v101, 0xffff0000, v101
	v_and_b32_e32 v105, 0xffff0000, v105
	v_fmac_f32_e32 v112, v108, v113
	v_fmac_f32_e32 v98, v109, v102
	v_fmac_f32_e32 v114, v110, v115
	v_fmac_f32_e32 v99, v111, v103
	v_fmac_f32_e32 v116, v88, v117
	v_fmac_f32_e32 v100, v89, v104
	v_fmac_f32_e32 v118, v90, v119
	v_fmac_f32_e32 v101, v91, v105
	v_cvt_pk_bf16_f32 v88, v112, v98
	v_cvt_pk_bf16_f32 v89, v114, v99
	v_cvt_pk_bf16_f32 v90, v116, v100
	v_cvt_pk_bf16_f32 v91, v118, v101
	global_store_dwordx4 v[92:93], v[88:91], off
	s_nop 1
	s_waitcnt vmcnt(19)
	v_mov_b32_e32 v88, v222
	v_mov_b32_e32 v89, v223
	v_mov_b32_e32 v90, v224
	v_mov_b32_e32 v91, v225
	s_nop 0
	s_nop 1
	v_mov_b32_e32 v92, v226
	v_mov_b32_e32 v93, v227
	v_mov_b32_e32 v94, v228
	v_mov_b32_e32 v95, v229
	s_mov_b64 s[98:99], 0xa0000
	v_lshl_add_u64 v[250:251], v[246:247], 0, s[98:99]
	global_load_dwordx4 v[222:225], v[250:251], off offset:256
	v_lshl_add_u64 v[252:253], v[248:249], 0, s[98:99]
	global_load_dwordx4 v[226:229], v[252:253], off offset:256
	v_exp_f32_e32 v98, v80
	v_exp_f32_e32 v99, v81
	v_or_b32_e32 v80, 48, v148
	v_ashrrev_i32_e32 v81, 31, v80
	v_add_f32_e32 v98, 1.0, v98
	v_add_f32_e32 v99, 1.0, v99
	v_rcp_f32_e32 v100, v86
	v_rcp_f32_e32 v101, v87
	v_rcp_f32_e32 v102, v98
	v_rcp_f32_e32 v103, v99
	v_lshlrev_b64 v[80:81], 11, v[80:81]
	v_lshl_add_u64 v[80:81], v[80:81], 0, v[146:147]
	v_lshlrev_b64 v[80:81], 1, v[80:81]
	v_lshl_add_u64 v[86:87], s[10:11], 0, v[80:81]
	v_lshl_add_u64 v[98:99], s[12:13], 0, v[80:81]
	v_exp_f32_e32 v28, v28
	v_exp_f32_e32 v29, v29
	v_exp_f32_e32 v30, v30
	v_exp_f32_e32 v31, v31
	v_exp_f32_e32 v24, v24
	v_exp_f32_e32 v25, v25
	v_exp_f32_e32 v26, v26
	v_exp_f32_e32 v27, v27
	v_add_f32_e32 v28, 1.0, v28
	v_add_f32_e32 v29, 1.0, v29
	v_add_f32_e32 v30, 1.0, v30
	v_add_f32_e32 v31, 1.0, v31
	v_add_f32_e32 v24, 1.0, v24
	v_add_f32_e32 v25, 1.0, v25
	v_add_f32_e32 v26, 1.0, v26
	v_add_f32_e32 v27, 1.0, v27
	v_rcp_f32_e32 v24, v24
	v_rcp_f32_e32 v25, v25
	v_rcp_f32_e32 v26, v26
	v_rcp_f32_e32 v27, v27
	v_mul_f32_e32 v20, 0xbfb8aa3b, v20
	v_mul_f32_e32 v21, 0xbfb8aa3b, v21
	v_mul_f32_e32 v22, 0xbfb8aa3b, v22
	v_mul_f32_e32 v23, 0xbfb8aa3b, v23
	v_mul_f32_e32 v16, 0xbfb8aa3b, v16
	v_mul_f32_e32 v17, 0xbfb8aa3b, v17
	v_mul_f32_e32 v18, 0xbfb8aa3b, v18
	v_mul_f32_e32 v19, 0xbfb8aa3b, v19
	v_exp_f32_e32 v20, v20
	v_exp_f32_e32 v21, v21
	v_exp_f32_e32 v22, v22
	v_exp_f32_e32 v23, v23
	v_exp_f32_e32 v16, v16
	v_exp_f32_e32 v17, v17
	v_exp_f32_e32 v18, v18
	v_exp_f32_e32 v19, v19
	v_add_f32_e32 v20, 1.0, v20
	v_add_f32_e32 v21, 1.0, v21
	v_add_f32_e32 v22, 1.0, v22
	v_add_f32_e32 v23, 1.0, v23
	v_add_f32_e32 v16, 1.0, v16
	v_add_f32_e32 v17, 1.0, v17
	v_add_f32_e32 v18, 1.0, v18
	v_add_f32_e32 v19, 1.0, v19
	v_rcp_f32_e32 v16, v16
	v_rcp_f32_e32 v17, v17
	v_rcp_f32_e32 v18, v18
	v_rcp_f32_e32 v19, v19
	v_mul_f32_e32 v12, 0xbfb8aa3b, v12
	v_mul_f32_e32 v13, 0xbfb8aa3b, v13
	v_mul_f32_e32 v14, 0xbfb8aa3b, v14
	v_mul_f32_e32 v15, 0xbfb8aa3b, v15
	v_mul_f32_e32 v8, 0xbfb8aa3b, v8
	v_mul_f32_e32 v9, 0xbfb8aa3b, v9
	v_mul_f32_e32 v10, 0xbfb8aa3b, v10
	v_mul_f32_e32 v11, 0xbfb8aa3b, v11
	v_exp_f32_e32 v12, v12
	v_exp_f32_e32 v13, v13
	v_exp_f32_e32 v14, v14
	v_exp_f32_e32 v15, v15
	v_exp_f32_e32 v8, v8
	v_exp_f32_e32 v9, v9
	v_exp_f32_e32 v10, v10
	v_lshlrev_b32_e32 v104, 16, v88
	v_lshlrev_b32_e32 v105, 16, v92
	v_and_b32_e32 v88, 0xffff0000, v88
	v_and_b32_e32 v92, 0xffff0000, v92
	v_lshlrev_b32_e32 v106, 16, v89
	v_lshlrev_b32_e32 v107, 16, v93
	v_and_b32_e32 v89, 0xffff0000, v89
	v_and_b32_e32 v93, 0xffff0000, v93
	v_lshlrev_b32_e32 v108, 16, v90
	v_lshlrev_b32_e32 v109, 16, v94
	v_and_b32_e32 v90, 0xffff0000, v90
	v_and_b32_e32 v94, 0xffff0000, v94
	v_lshlrev_b32_e32 v110, 16, v91
	v_lshlrev_b32_e32 v111, 16, v95
	v_and_b32_e32 v91, 0xffff0000, v91
	v_and_b32_e32 v95, 0xffff0000, v95
	v_fmac_f32_e32 v104, v84, v105
	v_fmac_f32_e32 v88, v85, v92
	v_fmac_f32_e32 v106, v100, v107
	v_fmac_f32_e32 v89, v101, v93
	v_fmac_f32_e32 v108, v102, v109
	v_fmac_f32_e32 v90, v103, v94
	v_fmac_f32_e32 v110, v82, v111
	v_fmac_f32_e32 v91, v83, v95
	v_cvt_pk_bf16_f32 v82, v104, v88
	v_cvt_pk_bf16_f32 v83, v106, v89
	v_cvt_pk_bf16_f32 v84, v108, v90
	v_cvt_pk_bf16_f32 v85, v110, v91
	global_store_dwordx4 v[96:97], v[82:85], off
	s_nop 1
	s_waitcnt vmcnt(20)
	v_mov_b32_e32 v82, v230
	v_mov_b32_e32 v83, v231
	v_mov_b32_e32 v84, v232
	v_mov_b32_e32 v85, v233
	s_nop 0
	s_nop 1
	v_mov_b32_e32 v86, v234
	v_mov_b32_e32 v87, v235
	v_mov_b32_e32 v88, v236
	v_mov_b32_e32 v89, v237
	s_mov_b64 s[98:99], 0xb0000
	v_lshl_add_u64 v[250:251], v[246:247], 0, s[98:99]
	global_load_dwordx4 v[230:233], v[250:251], off
	v_lshl_add_u64 v[252:253], v[248:249], 0, s[98:99]
	global_load_dwordx4 v[234:237], v[252:253], off
	v_rcp_f32_e32 v92, v76
	v_rcp_f32_e32 v93, v77
	v_rcp_f32_e32 v94, v78
	v_rcp_f32_e32 v95, v79
	v_lshl_add_u64 v[76:77], s[14:15], 0, v[80:81]
	v_or_b32_e32 v80, 0x100, v80
	v_lshl_add_u64 v[78:79], s[10:11], 0, v[80:81]
	v_lshl_add_u64 v[90:91], s[12:13], 0, v[80:81]
	v_lshl_add_u64 v[80:81], s[14:15], 0, v[80:81]
	v_exp_f32_e32 v11, v11
	v_add_f32_e32 v12, 1.0, v12
	v_add_f32_e32 v13, 1.0, v13
	v_add_f32_e32 v14, 1.0, v14
	v_add_f32_e32 v15, 1.0, v15
	v_add_f32_e32 v8, 1.0, v8
	v_add_f32_e32 v9, 1.0, v9
	v_add_f32_e32 v10, 1.0, v10
	v_add_f32_e32 v11, 1.0, v11
	v_rcp_f32_e32 v8, v8
	v_rcp_f32_e32 v9, v9
	v_rcp_f32_e32 v10, v10
	v_rcp_f32_e32 v11, v11
	v_mul_f32_e32 v4, 0xbfb8aa3b, v4
	v_mul_f32_e32 v5, 0xbfb8aa3b, v5
	v_mul_f32_e32 v6, 0xbfb8aa3b, v6
	v_mul_f32_e32 v7, 0xbfb8aa3b, v7
	v_mul_f32_e32 v0, 0xbfb8aa3b, v0
	v_mul_f32_e32 v1, 0xbfb8aa3b, v1
	v_mul_f32_e32 v2, 0xbfb8aa3b, v2
	v_mul_f32_e32 v3, 0xbfb8aa3b, v3
	v_exp_f32_e32 v4, v4
	v_exp_f32_e32 v5, v5
	v_exp_f32_e32 v6, v6
	v_exp_f32_e32 v7, v7
	v_exp_f32_e32 v0, v0
	v_exp_f32_e32 v1, v1
	v_exp_f32_e32 v2, v2
	v_exp_f32_e32 v3, v3
	v_add_f32_e32 v4, 1.0, v4
	v_add_f32_e32 v5, 1.0, v5
	v_add_f32_e32 v6, 1.0, v6
	v_add_f32_e32 v7, 1.0, v7
	v_add_f32_e32 v0, 1.0, v0
	v_add_f32_e32 v1, 1.0, v1
	v_add_f32_e32 v2, 1.0, v2
	v_add_f32_e32 v3, 1.0, v3
	v_rcp_f32_e32 v6, v6
	v_rcp_f32_e32 v7, v7
	v_rcp_f32_e32 v0, v0
	v_rcp_f32_e32 v1, v1
	v_rcp_f32_e32 v2, v2
	v_rcp_f32_e32 v3, v3
	s_andn2_b64 vcc, exec, s[0:1]
	s_mov_b64 s[0:1], -1
	v_lshlrev_b32_e32 v96, 16, v82
	v_lshlrev_b32_e32 v97, 16, v86
	v_and_b32_e32 v82, 0xffff0000, v82
	v_and_b32_e32 v86, 0xffff0000, v86
	v_lshlrev_b32_e32 v98, 16, v83
	v_lshlrev_b32_e32 v99, 16, v87
	v_and_b32_e32 v83, 0xffff0000, v83
	v_and_b32_e32 v87, 0xffff0000, v87
	v_lshlrev_b32_e32 v100, 16, v84
	v_lshlrev_b32_e32 v101, 16, v88
	v_and_b32_e32 v84, 0xffff0000, v84
	v_and_b32_e32 v88, 0xffff0000, v88
	v_lshlrev_b32_e32 v102, 16, v85
	v_lshlrev_b32_e32 v103, 16, v89
	v_and_b32_e32 v85, 0xffff0000, v85
	v_and_b32_e32 v89, 0xffff0000, v89
	v_fmac_f32_e32 v96, v92, v97
	v_fmac_f32_e32 v82, v93, v86
	v_fmac_f32_e32 v98, v94, v99
	v_fmac_f32_e32 v83, v95, v87
	v_fmac_f32_e32 v100, v72, v101
	v_fmac_f32_e32 v84, v73, v88
	v_fmac_f32_e32 v102, v74, v103
	v_fmac_f32_e32 v85, v75, v89
	v_cvt_pk_bf16_f32 v72, v96, v82
	v_cvt_pk_bf16_f32 v73, v98, v83
	v_cvt_pk_bf16_f32 v74, v100, v84
	v_cvt_pk_bf16_f32 v75, v102, v85
	global_store_dwordx4 v[76:77], v[72:75], off
	s_nop 1
	s_waitcnt vmcnt(21)
	v_mov_b32_e32 v72, v238
	v_mov_b32_e32 v73, v239
	v_mov_b32_e32 v74, v240
	v_mov_b32_e32 v75, v241
	s_nop 0
	s_nop 1
	v_mov_b32_e32 v76, v242
	v_mov_b32_e32 v77, v243
	v_mov_b32_e32 v78, v244
	v_mov_b32_e32 v79, v245
	s_mov_b64 s[98:99], 0xb0000
	v_lshl_add_u64 v[250:251], v[246:247], 0, s[98:99]
	global_load_dwordx4 v[238:241], v[250:251], off offset:256
	v_lshl_add_u64 v[252:253], v[248:249], 0, s[98:99]
	global_load_dwordx4 v[242:245], v[252:253], off offset:256
	v_rcp_f32_e32 v84, v68
	v_rcp_f32_e32 v85, v69
	v_rcp_f32_e32 v86, v70
	v_rcp_f32_e32 v87, v71
	v_lshl_add_u64 v[82:83], v[144:145], 0, s[6:7]
	v_lshl_add_u64 v[68:69], s[10:11], 0, v[82:83]
	v_lshl_add_u64 v[70:71], s[12:13], 0, v[82:83]
	v_lshlrev_b32_e32 v88, 16, v72
	v_lshlrev_b32_e32 v89, 16, v76
	v_and_b32_e32 v72, 0xffff0000, v72
	v_and_b32_e32 v76, 0xffff0000, v76
	v_lshlrev_b32_e32 v90, 16, v73
	v_lshlrev_b32_e32 v91, 16, v77
	v_and_b32_e32 v73, 0xffff0000, v73
	v_and_b32_e32 v77, 0xffff0000, v77
	v_lshlrev_b32_e32 v92, 16, v74
	v_lshlrev_b32_e32 v93, 16, v78
	v_and_b32_e32 v74, 0xffff0000, v74
	v_and_b32_e32 v78, 0xffff0000, v78
	v_lshlrev_b32_e32 v94, 16, v75
	v_lshlrev_b32_e32 v95, 16, v79
	v_and_b32_e32 v75, 0xffff0000, v75
	v_and_b32_e32 v79, 0xffff0000, v79
	v_fmac_f32_e32 v88, v84, v89
	v_fmac_f32_e32 v72, v85, v76
	v_fmac_f32_e32 v90, v86, v91
	v_fmac_f32_e32 v73, v87, v77
	v_fmac_f32_e32 v92, v64, v93
	v_fmac_f32_e32 v74, v65, v78
	v_fmac_f32_e32 v94, v66, v95
	v_fmac_f32_e32 v75, v67, v79
	v_cvt_pk_bf16_f32 v64, v88, v72
	v_cvt_pk_bf16_f32 v65, v90, v73
	v_cvt_pk_bf16_f32 v66, v92, v74
	v_cvt_pk_bf16_f32 v67, v94, v75
	global_store_dwordx4 v[80:81], v[64:67], off
	s_nop 1
	s_waitcnt vmcnt(22)
	v_mov_b32_e32 v64, v180
	v_mov_b32_e32 v65, v181
	v_mov_b32_e32 v66, v182
	v_mov_b32_e32 v67, v183
	s_nop 0
	s_nop 1
	v_mov_b32_e32 v68, v184
	v_mov_b32_e32 v69, v185
	v_mov_b32_e32 v70, v186
	v_mov_b32_e32 v71, v187
	v_rcp_f32_e32 v76, v60
	v_rcp_f32_e32 v77, v61
	v_rcp_f32_e32 v78, v62
	v_rcp_f32_e32 v79, v63
	v_lshl_add_u64 v[72:73], v[144:145], 0, s[20:21]
	v_lshl_add_u64 v[60:61], s[14:15], 0, v[82:83]
	v_lshl_add_u64 v[62:63], s[10:11], 0, v[72:73]
	v_lshl_add_u64 v[74:75], s[12:13], 0, v[72:73]
	v_lshlrev_b32_e32 v80, 16, v64
	v_lshlrev_b32_e32 v81, 16, v68
	v_and_b32_e32 v64, 0xffff0000, v64
	v_and_b32_e32 v68, 0xffff0000, v68
	v_lshlrev_b32_e32 v82, 16, v65
	v_lshlrev_b32_e32 v83, 16, v69
	v_and_b32_e32 v65, 0xffff0000, v65
	v_and_b32_e32 v69, 0xffff0000, v69
	v_lshlrev_b32_e32 v84, 16, v66
	v_lshlrev_b32_e32 v85, 16, v70
	v_and_b32_e32 v66, 0xffff0000, v66
	v_and_b32_e32 v70, 0xffff0000, v70
	v_lshlrev_b32_e32 v86, 16, v67
	v_lshlrev_b32_e32 v87, 16, v71
	v_and_b32_e32 v67, 0xffff0000, v67
	v_and_b32_e32 v71, 0xffff0000, v71
	v_fmac_f32_e32 v80, v76, v81
	v_fmac_f32_e32 v64, v77, v68
	v_fmac_f32_e32 v82, v78, v83
	v_fmac_f32_e32 v65, v79, v69
	v_fmac_f32_e32 v84, v56, v85
	v_fmac_f32_e32 v66, v57, v70
	v_fmac_f32_e32 v86, v58, v87
	v_fmac_f32_e32 v67, v59, v71
	v_cvt_pk_bf16_f32 v56, v80, v64
	v_cvt_pk_bf16_f32 v57, v82, v65
	v_cvt_pk_bf16_f32 v58, v84, v66
	v_cvt_pk_bf16_f32 v59, v86, v67
	global_store_dwordx4 v[60:61], v[56:59], off
	s_nop 1
	s_waitcnt vmcnt(20)
	v_mov_b32_e32 v56, v188
	v_mov_b32_e32 v57, v189
	v_mov_b32_e32 v58, v190
	v_mov_b32_e32 v59, v191
	s_nop 0
	s_nop 1
	v_mov_b32_e32 v60, v192
	v_mov_b32_e32 v61, v193
	v_mov_b32_e32 v62, v194
	v_mov_b32_e32 v63, v195
	v_rcp_f32_e32 v68, v52
	v_rcp_f32_e32 v69, v53
	v_rcp_f32_e32 v70, v54
	v_rcp_f32_e32 v71, v55
	v_lshl_add_u64 v[64:65], v[144:145], 0, s[22:23]
	v_lshl_add_u64 v[52:53], s[14:15], 0, v[72:73]
	v_lshl_add_u64 v[54:55], s[10:11], 0, v[64:65]
	v_lshl_add_u64 v[66:67], s[12:13], 0, v[64:65]
	v_lshlrev_b32_e32 v72, 16, v56
	v_lshlrev_b32_e32 v73, 16, v60
	v_and_b32_e32 v56, 0xffff0000, v56
	v_and_b32_e32 v60, 0xffff0000, v60
	v_lshlrev_b32_e32 v74, 16, v57
	v_lshlrev_b32_e32 v75, 16, v61
	v_and_b32_e32 v57, 0xffff0000, v57
	v_and_b32_e32 v61, 0xffff0000, v61
	v_lshlrev_b32_e32 v76, 16, v58
	v_lshlrev_b32_e32 v77, 16, v62
	v_and_b32_e32 v58, 0xffff0000, v58
	v_and_b32_e32 v62, 0xffff0000, v62
	v_lshlrev_b32_e32 v78, 16, v59
	v_lshlrev_b32_e32 v79, 16, v63
	v_and_b32_e32 v59, 0xffff0000, v59
	v_and_b32_e32 v63, 0xffff0000, v63
	v_fmac_f32_e32 v72, v68, v73
	v_fmac_f32_e32 v56, v69, v60
	v_fmac_f32_e32 v74, v70, v75
	v_fmac_f32_e32 v57, v71, v61
	v_fmac_f32_e32 v76, v48, v77
	v_fmac_f32_e32 v58, v49, v62
	v_fmac_f32_e32 v78, v50, v79
	v_fmac_f32_e32 v59, v51, v63
	v_cvt_pk_bf16_f32 v48, v72, v56
	v_cvt_pk_bf16_f32 v49, v74, v57
	v_cvt_pk_bf16_f32 v50, v76, v58
	v_cvt_pk_bf16_f32 v51, v78, v59
	global_store_dwordx4 v[52:53], v[48:51], off
	s_nop 1
	s_waitcnt vmcnt(18)
	v_mov_b32_e32 v48, v196
	v_mov_b32_e32 v49, v197
	v_mov_b32_e32 v50, v198
	v_mov_b32_e32 v51, v199
	s_nop 0
	s_nop 1
	v_mov_b32_e32 v52, v200
	v_mov_b32_e32 v53, v201
	v_mov_b32_e32 v54, v202
	v_mov_b32_e32 v55, v203
	v_rcp_f32_e32 v60, v44
	v_rcp_f32_e32 v61, v45
	v_rcp_f32_e32 v62, v46
	v_rcp_f32_e32 v63, v47
	v_lshl_add_u64 v[56:57], v[144:145], 0, s[24:25]
	v_lshl_add_u64 v[44:45], s[14:15], 0, v[64:65]
	v_lshl_add_u64 v[46:47], s[10:11], 0, v[56:57]
	v_lshl_add_u64 v[58:59], s[12:13], 0, v[56:57]
	v_lshlrev_b32_e32 v64, 16, v48
	v_lshlrev_b32_e32 v65, 16, v52
	v_and_b32_e32 v48, 0xffff0000, v48
	v_and_b32_e32 v52, 0xffff0000, v52
	v_lshlrev_b32_e32 v66, 16, v49
	v_lshlrev_b32_e32 v67, 16, v53
	v_and_b32_e32 v49, 0xffff0000, v49
	v_and_b32_e32 v53, 0xffff0000, v53
	v_lshlrev_b32_e32 v68, 16, v50
	v_lshlrev_b32_e32 v69, 16, v54
	v_and_b32_e32 v50, 0xffff0000, v50
	v_and_b32_e32 v54, 0xffff0000, v54
	v_lshlrev_b32_e32 v70, 16, v51
	v_lshlrev_b32_e32 v71, 16, v55
	v_and_b32_e32 v51, 0xffff0000, v51
	v_and_b32_e32 v55, 0xffff0000, v55
	v_fmac_f32_e32 v64, v60, v65
	v_fmac_f32_e32 v48, v61, v52
	v_fmac_f32_e32 v66, v62, v67
	v_fmac_f32_e32 v49, v63, v53
	v_fmac_f32_e32 v68, v40, v69
	v_fmac_f32_e32 v50, v41, v54
	v_fmac_f32_e32 v70, v42, v71
	v_fmac_f32_e32 v51, v43, v55
	v_cvt_pk_bf16_f32 v40, v64, v48
	v_cvt_pk_bf16_f32 v41, v66, v49
	v_cvt_pk_bf16_f32 v42, v68, v50
	v_cvt_pk_bf16_f32 v43, v70, v51
	global_store_dwordx4 v[44:45], v[40:43], off
	s_nop 1
	s_waitcnt vmcnt(16)
	v_mov_b32_e32 v40, v204
	v_mov_b32_e32 v41, v205
	v_mov_b32_e32 v42, v206
	v_mov_b32_e32 v43, v207
	s_nop 0
	s_nop 1
	v_mov_b32_e32 v44, v208
	v_mov_b32_e32 v45, v209
	v_mov_b32_e32 v46, v210
	v_mov_b32_e32 v47, v211
	v_rcp_f32_e32 v52, v36
	v_rcp_f32_e32 v53, v37
	v_rcp_f32_e32 v54, v38
	v_rcp_f32_e32 v55, v39
	v_lshl_add_u64 v[48:49], v[144:145], 0, s[26:27]
	v_lshl_add_u64 v[36:37], s[14:15], 0, v[56:57]
	v_lshl_add_u64 v[38:39], s[10:11], 0, v[48:49]
	v_lshl_add_u64 v[50:51], s[12:13], 0, v[48:49]
	v_lshlrev_b32_e32 v56, 16, v40
	v_lshlrev_b32_e32 v57, 16, v44
	v_and_b32_e32 v40, 0xffff0000, v40
	v_and_b32_e32 v44, 0xffff0000, v44
	v_lshlrev_b32_e32 v58, 16, v41
	v_lshlrev_b32_e32 v59, 16, v45
	v_and_b32_e32 v41, 0xffff0000, v41
	v_and_b32_e32 v45, 0xffff0000, v45
	v_lshlrev_b32_e32 v60, 16, v42
	v_lshlrev_b32_e32 v61, 16, v46
	v_and_b32_e32 v42, 0xffff0000, v42
	v_and_b32_e32 v46, 0xffff0000, v46
	v_lshlrev_b32_e32 v62, 16, v43
	v_lshlrev_b32_e32 v63, 16, v47
	v_and_b32_e32 v43, 0xffff0000, v43
	v_and_b32_e32 v47, 0xffff0000, v47
	v_fmac_f32_e32 v56, v52, v57
	v_fmac_f32_e32 v40, v53, v44
	v_fmac_f32_e32 v58, v54, v59
	v_fmac_f32_e32 v41, v55, v45
	v_fmac_f32_e32 v60, v32, v61
	v_fmac_f32_e32 v42, v33, v46
	v_fmac_f32_e32 v62, v34, v63
	v_fmac_f32_e32 v43, v35, v47
	v_cvt_pk_bf16_f32 v32, v56, v40
	v_cvt_pk_bf16_f32 v33, v58, v41
	v_cvt_pk_bf16_f32 v34, v60, v42
	v_cvt_pk_bf16_f32 v35, v62, v43
	global_store_dwordx4 v[36:37], v[32:35], off
	s_nop 1
	s_waitcnt vmcnt(14)
	v_mov_b32_e32 v32, v214
	v_mov_b32_e32 v33, v215
	v_mov_b32_e32 v34, v216
	v_mov_b32_e32 v35, v217
	s_nop 0
	s_nop 1
	v_mov_b32_e32 v36, v218
	v_mov_b32_e32 v37, v219
	v_mov_b32_e32 v38, v220
	v_mov_b32_e32 v39, v221
	v_rcp_f32_e32 v44, v28
	v_rcp_f32_e32 v45, v29
	v_rcp_f32_e32 v46, v30
	v_rcp_f32_e32 v47, v31
	v_lshl_add_u64 v[40:41], v[144:145], 0, s[28:29]
	v_lshl_add_u64 v[28:29], s[14:15], 0, v[48:49]
	v_lshl_add_u64 v[30:31], s[10:11], 0, v[40:41]
	v_lshl_add_u64 v[42:43], s[12:13], 0, v[40:41]
	v_lshlrev_b32_e32 v48, 16, v32
	v_lshlrev_b32_e32 v49, 16, v36
	v_and_b32_e32 v32, 0xffff0000, v32
	v_and_b32_e32 v36, 0xffff0000, v36
	v_lshlrev_b32_e32 v50, 16, v33
	v_lshlrev_b32_e32 v51, 16, v37
	v_and_b32_e32 v33, 0xffff0000, v33
	v_and_b32_e32 v37, 0xffff0000, v37
	v_lshlrev_b32_e32 v52, 16, v34
	v_lshlrev_b32_e32 v53, 16, v38
	v_and_b32_e32 v34, 0xffff0000, v34
	v_and_b32_e32 v38, 0xffff0000, v38
	v_lshlrev_b32_e32 v54, 16, v35
	v_lshlrev_b32_e32 v55, 16, v39
	v_and_b32_e32 v35, 0xffff0000, v35
	v_and_b32_e32 v39, 0xffff0000, v39
	v_fmac_f32_e32 v48, v44, v49
	v_fmac_f32_e32 v32, v45, v36
	v_fmac_f32_e32 v50, v46, v51
	v_fmac_f32_e32 v33, v47, v37
	v_fmac_f32_e32 v52, v24, v53
	v_fmac_f32_e32 v34, v25, v38
	v_fmac_f32_e32 v54, v26, v55
	v_fmac_f32_e32 v35, v27, v39
	v_cvt_pk_bf16_f32 v24, v48, v32
	v_cvt_pk_bf16_f32 v25, v50, v33
	v_cvt_pk_bf16_f32 v26, v52, v34
	v_cvt_pk_bf16_f32 v27, v54, v35
	global_store_dwordx4 v[28:29], v[24:27], off
	s_nop 1
	s_waitcnt vmcnt(12)
	v_mov_b32_e32 v24, v222
	v_mov_b32_e32 v25, v223
	v_mov_b32_e32 v26, v224
	v_mov_b32_e32 v27, v225
	s_nop 0
	s_nop 1
	v_mov_b32_e32 v28, v226
	v_mov_b32_e32 v29, v227
	v_mov_b32_e32 v30, v228
	v_mov_b32_e32 v31, v229
	v_rcp_f32_e32 v36, v20
	v_rcp_f32_e32 v37, v21
	v_rcp_f32_e32 v38, v22
	v_rcp_f32_e32 v39, v23
	v_lshl_add_u64 v[32:33], v[144:145], 0, s[30:31]
	v_lshl_add_u64 v[20:21], s[14:15], 0, v[40:41]
	v_lshl_add_u64 v[22:23], s[10:11], 0, v[32:33]
	v_lshl_add_u64 v[34:35], s[12:13], 0, v[32:33]
	v_lshlrev_b32_e32 v40, 16, v24
	v_lshlrev_b32_e32 v41, 16, v28
	v_and_b32_e32 v24, 0xffff0000, v24
	v_and_b32_e32 v28, 0xffff0000, v28
	v_lshlrev_b32_e32 v42, 16, v25
	v_lshlrev_b32_e32 v43, 16, v29
	v_and_b32_e32 v25, 0xffff0000, v25
	v_and_b32_e32 v29, 0xffff0000, v29
	v_lshlrev_b32_e32 v44, 16, v26
	v_lshlrev_b32_e32 v45, 16, v30
	v_and_b32_e32 v26, 0xffff0000, v26
	v_and_b32_e32 v30, 0xffff0000, v30
	v_lshlrev_b32_e32 v46, 16, v27
	v_lshlrev_b32_e32 v47, 16, v31
	v_and_b32_e32 v27, 0xffff0000, v27
	v_and_b32_e32 v31, 0xffff0000, v31
	v_fmac_f32_e32 v40, v36, v41
	v_fmac_f32_e32 v24, v37, v28
	v_fmac_f32_e32 v42, v38, v43
	v_fmac_f32_e32 v25, v39, v29
	v_fmac_f32_e32 v44, v16, v45
	v_fmac_f32_e32 v26, v17, v30
	v_fmac_f32_e32 v46, v18, v47
	v_fmac_f32_e32 v27, v19, v31
	v_cvt_pk_bf16_f32 v16, v40, v24
	v_cvt_pk_bf16_f32 v17, v42, v25
	v_cvt_pk_bf16_f32 v18, v44, v26
	v_cvt_pk_bf16_f32 v19, v46, v27
	global_store_dwordx4 v[20:21], v[16:19], off
	s_nop 1
	s_waitcnt vmcnt(10)
	v_mov_b32_e32 v16, v230
	v_mov_b32_e32 v17, v231
	v_mov_b32_e32 v18, v232
	v_mov_b32_e32 v19, v233
	s_nop 0
	s_nop 1
	v_mov_b32_e32 v20, v234
	v_mov_b32_e32 v21, v235
	v_mov_b32_e32 v22, v236
	v_mov_b32_e32 v23, v237
	v_rcp_f32_e32 v28, v12
	v_rcp_f32_e32 v29, v13
	v_rcp_f32_e32 v30, v14
	v_rcp_f32_e32 v31, v15
	v_lshl_add_u64 v[24:25], v[144:145], 0, s[36:37]
	v_lshl_add_u64 v[12:13], s[14:15], 0, v[32:33]
	v_lshl_add_u64 v[14:15], s[10:11], 0, v[24:25]
	v_lshl_add_u64 v[26:27], s[12:13], 0, v[24:25]
	v_lshlrev_b32_e32 v32, 16, v16
	v_lshlrev_b32_e32 v33, 16, v20
	v_and_b32_e32 v16, 0xffff0000, v16
	v_and_b32_e32 v20, 0xffff0000, v20
	v_lshlrev_b32_e32 v34, 16, v17
	v_lshlrev_b32_e32 v35, 16, v21
	v_and_b32_e32 v17, 0xffff0000, v17
	v_and_b32_e32 v21, 0xffff0000, v21
	v_lshlrev_b32_e32 v36, 16, v18
	v_lshlrev_b32_e32 v37, 16, v22
	v_and_b32_e32 v18, 0xffff0000, v18
	v_and_b32_e32 v22, 0xffff0000, v22
	v_lshlrev_b32_e32 v38, 16, v19
	v_lshlrev_b32_e32 v39, 16, v23
	v_and_b32_e32 v19, 0xffff0000, v19
	v_and_b32_e32 v23, 0xffff0000, v23
	v_fmac_f32_e32 v32, v28, v33
	v_fmac_f32_e32 v16, v29, v20
	v_fmac_f32_e32 v34, v30, v35
	v_fmac_f32_e32 v17, v31, v21
	v_fmac_f32_e32 v36, v8, v37
	v_fmac_f32_e32 v18, v9, v22
	v_fmac_f32_e32 v38, v10, v39
	v_fmac_f32_e32 v19, v11, v23
	v_cvt_pk_bf16_f32 v8, v32, v16
	v_cvt_pk_bf16_f32 v9, v34, v17
	v_cvt_pk_bf16_f32 v10, v36, v18
	v_cvt_pk_bf16_f32 v11, v38, v19
	global_store_dwordx4 v[12:13], v[8:11], off
	s_nop 1
	s_waitcnt vmcnt(8)
	v_mov_b32_e32 v8, v238
	v_mov_b32_e32 v9, v239
	v_mov_b32_e32 v10, v240
	v_mov_b32_e32 v11, v241
	s_nop 0
	s_nop 1
	v_mov_b32_e32 v12, v242
	v_mov_b32_e32 v13, v243
	v_mov_b32_e32 v14, v244
	v_mov_b32_e32 v15, v245
	v_rcp_f32_e32 v16, v4
	v_rcp_f32_e32 v17, v5
	v_lshl_add_u64 v[4:5], s[14:15], 0, v[24:25]
	v_lshlrev_b32_e32 v18, 16, v8
	v_lshlrev_b32_e32 v19, 16, v12
	v_and_b32_e32 v8, 0xffff0000, v8
	v_and_b32_e32 v12, 0xffff0000, v12
	v_lshlrev_b32_e32 v20, 16, v9
	v_lshlrev_b32_e32 v21, 16, v13
	v_and_b32_e32 v9, 0xffff0000, v9
	v_and_b32_e32 v13, 0xffff0000, v13
	v_lshlrev_b32_e32 v22, 16, v10
	v_lshlrev_b32_e32 v23, 16, v14
	v_and_b32_e32 v10, 0xffff0000, v10
	v_and_b32_e32 v14, 0xffff0000, v14
	v_lshlrev_b32_e32 v24, 16, v11
	v_lshlrev_b32_e32 v25, 16, v15
	v_and_b32_e32 v11, 0xffff0000, v11
	v_and_b32_e32 v15, 0xffff0000, v15
	v_fmac_f32_e32 v18, v16, v19
	v_fmac_f32_e32 v8, v17, v12
	v_fmac_f32_e32 v20, v6, v21
	v_fmac_f32_e32 v9, v7, v13
	v_fmac_f32_e32 v22, v0, v23
	v_fmac_f32_e32 v10, v1, v14
	v_fmac_f32_e32 v24, v2, v25
	v_fmac_f32_e32 v11, v3, v15
	v_cvt_pk_bf16_f32 v0, v18, v8
	v_cvt_pk_bf16_f32 v1, v20, v9
	v_cvt_pk_bf16_f32 v2, v22, v10
	v_cvt_pk_bf16_f32 v3, v24, v11
	global_store_dwordx4 v[4:5], v[0:3], off
	s_cbranch_vccnz .LBB0_1233
	s_andn2_b64 vcc, exec, s[8:9]
	s_cbranch_vccnz .LBB0_1232
	s_barrier
	s_branch .LBB0_1232

.LBB0_2185:
	v_lshl_add_u32 v148, s38, 8, v150
	v_lshl_or_b32 v146, s58, 8, v152
	v_ashrrev_i32_e32 v149, 31, v148
	v_ashrrev_i32_e32 v147, 31, v146
	v_lshlrev_b64 v[144:145], 11, v[148:149]
	v_lshl_add_u64 v[144:145], v[144:145], 0, v[146:147]
	v_lshlrev_b64 v[164:165], 1, v[144:145]
	v_lshl_add_u64 v[156:157], s[10:11], 0, v[164:165]
	v_lshl_add_u64 v[160:161], s[8:9], 0, v[164:165]
	v_mov_b32_e32 v246, v156
	v_mov_b32_e32 v247, v157
	v_mov_b32_e32 v248, v160
	v_mov_b32_e32 v249, v161
	global_load_dwordx4 v[180:183], v[246:247], off
	global_load_dwordx4 v[184:187], v[248:249], off
	global_load_dwordx4 v[188:191], v[246:247], off offset:256
	global_load_dwordx4 v[192:195], v[248:249], off offset:256
	s_mov_b64 s[98:99], 0x10000
	v_lshl_add_u64 v[250:251], v[246:247], 0, s[98:99]
	global_load_dwordx4 v[196:199], v[250:251], off
	v_lshl_add_u64 v[252:253], v[248:249], 0, s[98:99]
	global_load_dwordx4 v[200:203], v[252:253], off
	s_mov_b64 s[98:99], 0x10000
	v_lshl_add_u64 v[250:251], v[246:247], 0, s[98:99]
	global_load_dwordx4 v[204:207], v[250:251], off offset:256
	v_lshl_add_u64 v[252:253], v[248:249], 0, s[98:99]
	global_load_dwordx4 v[208:211], v[252:253], off offset:256
	s_mov_b64 s[98:99], 0x20000
	v_lshl_add_u64 v[250:251], v[246:247], 0, s[98:99]
	global_load_dwordx4 v[214:217], v[250:251], off
	v_lshl_add_u64 v[252:253], v[248:249], 0, s[98:99]
	global_load_dwordx4 v[218:221], v[252:253], off
	s_mov_b64 s[98:99], 0x20000
	v_lshl_add_u64 v[250:251], v[246:247], 0, s[98:99]
	global_load_dwordx4 v[222:225], v[250:251], off offset:256
	v_lshl_add_u64 v[252:253], v[248:249], 0, s[98:99]
	global_load_dwordx4 v[226:229], v[252:253], off offset:256
	s_mov_b64 s[98:99], 0x30000
	v_lshl_add_u64 v[250:251], v[246:247], 0, s[98:99]
	global_load_dwordx4 v[230:233], v[250:251], off
	v_lshl_add_u64 v[252:253], v[248:249], 0, s[98:99]
	global_load_dwordx4 v[234:237], v[252:253], off
	s_mov_b64 s[98:99], 0x30000
	v_lshl_add_u64 v[250:251], v[246:247], 0, s[98:99]
	global_load_dwordx4 v[238:241], v[250:251], off offset:256
	v_lshl_add_u64 v[252:253], v[248:249], 0, s[98:99]
	global_load_dwordx4 v[242:245], v[252:253], off offset:256
	s_nop 1
	s_waitcnt vmcnt(14)
	v_mov_b32_e32 v156, v180
	v_mov_b32_e32 v157, v181
	v_mov_b32_e32 v158, v182
	v_mov_b32_e32 v159, v183
	v_mul_f32_e32 v124, 0xbfb8aa3b, v124
	s_nop 1
	v_mov_b32_e32 v160, v184
	v_mov_b32_e32 v161, v185
	v_mov_b32_e32 v162, v186
	v_mov_b32_e32 v163, v187
	s_mov_b64 s[98:99], 0x80000
	v_lshl_add_u64 v[250:251], v[246:247], 0, s[98:99]
	global_load_dwordx4 v[180:183], v[250:251], off
	v_lshl_add_u64 v[252:253], v[248:249], 0, s[98:99]
	global_load_dwordx4 v[184:187], v[252:253], off
	v_mul_f32_e32 v125, 0xbfb8aa3b, v125
	v_mul_f32_e32 v126, 0xbfb8aa3b, v126
	v_mul_f32_e32 v127, 0xbfb8aa3b, v127
	v_mul_f32_e32 v120, 0xbfb8aa3b, v120
	v_mul_f32_e32 v121, 0xbfb8aa3b, v121
	v_mul_f32_e32 v122, 0xbfb8aa3b, v122
	v_mul_f32_e32 v123, 0xbfb8aa3b, v123
	v_exp_f32_e32 v124, v124
	v_exp_f32_e32 v125, v125
	v_exp_f32_e32 v126, v126
	v_exp_f32_e32 v127, v127
	v_exp_f32_e32 v120, v120
	v_exp_f32_e32 v121, v121
	v_exp_f32_e32 v122, v122
	v_exp_f32_e32 v123, v123
	v_add_f32_e32 v124, 1.0, v124
	v_add_f32_e32 v125, 1.0, v125
	v_add_f32_e32 v126, 1.0, v126
	v_add_f32_e32 v127, 1.0, v127
	v_add_f32_e32 v149, 1.0, v120
	v_add_f32_e32 v168, 1.0, v121
	v_add_f32_e32 v169, 1.0, v122
	v_add_f32_e32 v170, 1.0, v123
	v_rcp_f32_e32 v120, v124
	v_rcp_f32_e32 v121, v125
	v_rcp_f32_e32 v122, v126
	v_rcp_f32_e32 v123, v127
	v_rcp_f32_e32 v124, v149
	v_rcp_f32_e32 v125, v168
	v_rcp_f32_e32 v126, v169
	v_rcp_f32_e32 v127, v170
	v_lshl_add_u64 v[166:167], v[144:145], 2, s[4:5]
	v_or_b32_e32 v164, 0x100, v164
	v_lshl_add_u64 v[168:169], s[10:11], 0, v[164:165]
	v_mul_f32_e32 v116, 0xbfb8aa3b, v116
	v_mul_f32_e32 v117, 0xbfb8aa3b, v117
	v_mul_f32_e32 v118, 0xbfb8aa3b, v118
	v_mul_f32_e32 v119, 0xbfb8aa3b, v119
	v_mul_f32_e32 v112, 0xbfb8aa3b, v112
	v_mul_f32_e32 v113, 0xbfb8aa3b, v113
	v_mul_f32_e32 v114, 0xbfb8aa3b, v114
	v_mul_f32_e32 v115, 0xbfb8aa3b, v115
	v_exp_f32_e32 v116, v116
	v_exp_f32_e32 v117, v117
	v_exp_f32_e32 v118, v118
	v_exp_f32_e32 v119, v119
	v_exp_f32_e32 v149, v112
	v_exp_f32_e32 v114, v114
	v_exp_f32_e32 v115, v115
	v_or_b32_e32 v112, 16, v148
	v_mul_f32_e32 v108, 0xbfb8aa3b, v108
	v_mul_f32_e32 v109, 0xbfb8aa3b, v109
	v_mul_f32_e32 v110, 0xbfb8aa3b, v110
	v_mul_f32_e32 v111, 0xbfb8aa3b, v111
	v_mul_f32_e32 v104, 0xbfb8aa3b, v104
	v_mul_f32_e32 v105, 0xbfb8aa3b, v105
	v_mul_f32_e32 v106, 0xbfb8aa3b, v106
	v_mul_f32_e32 v107, 0xbfb8aa3b, v107
	v_exp_f32_e32 v108, v108
	v_exp_f32_e32 v109, v109
	v_exp_f32_e32 v110, v110
	v_exp_f32_e32 v111, v111
	v_exp_f32_e32 v104, v104
	v_exp_f32_e32 v105, v105
	v_exp_f32_e32 v106, v106
	v_exp_f32_e32 v107, v107
	v_add_f32_e32 v108, 1.0, v108
	v_add_f32_e32 v109, 1.0, v109
	v_add_f32_e32 v110, 1.0, v110
	v_add_f32_e32 v111, 1.0, v111
	v_mul_f32_e32 v100, 0xbfb8aa3b, v100
	v_mul_f32_e32 v101, 0xbfb8aa3b, v101
	v_mul_f32_e32 v102, 0xbfb8aa3b, v102
	v_mul_f32_e32 v103, 0xbfb8aa3b, v103
	v_mul_f32_e32 v96, 0xbfb8aa3b, v96
	v_mul_f32_e32 v97, 0xbfb8aa3b, v97
	v_mul_f32_e32 v98, 0xbfb8aa3b, v98
	v_lshlrev_b32_e32 v174, 16, v156
	v_and_b32_e32 v175, 0xffff0000, v156
	v_lshlrev_b32_e32 v176, 16, v160
	v_and_b32_e32 v177, 0xffff0000, v160
	v_lshlrev_b32_e32 v156, 16, v157
	v_and_b32_e32 v157, 0xffff0000, v157
	v_lshlrev_b32_e32 v160, 16, v161
	v_and_b32_e32 v161, 0xffff0000, v161
	v_lshlrev_b32_e32 v170, 16, v158
	v_and_b32_e32 v171, 0xffff0000, v158
	v_lshlrev_b32_e32 v172, 16, v162
	v_and_b32_e32 v173, 0xffff0000, v162
	v_lshlrev_b32_e32 v158, 16, v159
	v_and_b32_e32 v159, 0xffff0000, v159
	v_lshlrev_b32_e32 v162, 16, v163
	v_and_b32_e32 v163, 0xffff0000, v163
	v_pk_fma_f32 v[124:125], v[124:125], v[174:175], v[176:177]
	v_pk_fma_f32 v[126:127], v[126:127], v[156:157], v[160:161]
	v_pk_fma_f32 v[120:121], v[120:121], v[170:171], v[172:173]
	v_pk_fma_f32 v[122:123], v[122:123], v[158:159], v[162:163]
	global_store_dwordx4 v[166:167], v[124:127], off
	global_store_dwordx4 v[166:167], v[120:123], off offset:16
	s_nop 1
	s_waitcnt vmcnt(16)
	v_mov_b32_e32 v120, v188
	v_mov_b32_e32 v121, v189
	v_mov_b32_e32 v122, v190
	v_mov_b32_e32 v123, v191
	v_lshl_add_u64 v[124:125], s[8:9], 0, v[164:165]
	s_nop 1
	v_mov_b32_e32 v124, v192
	v_mov_b32_e32 v125, v193
	v_mov_b32_e32 v126, v194
	v_mov_b32_e32 v127, v195
	s_mov_b64 s[98:99], 0x80000
	v_lshl_add_u64 v[250:251], v[246:247], 0, s[98:99]
	global_load_dwordx4 v[188:191], v[250:251], off offset:256
	v_lshl_add_u64 v[252:253], v[248:249], 0, s[98:99]
	global_load_dwordx4 v[192:195], v[252:253], off offset:256
	v_exp_f32_e32 v158, v113
	v_ashrrev_i32_e32 v113, 31, v112
	v_lshlrev_b64 v[112:113], 11, v[112:113]
	v_lshl_add_u64 v[156:157], v[112:113], 0, v[146:147]
	v_add_f32_e32 v112, 1.0, v116
	v_add_f32_e32 v113, 1.0, v117
	v_add_f32_e32 v116, 1.0, v118
	v_add_f32_e32 v117, 1.0, v119
	v_add_f32_e32 v118, 1.0, v149
	v_add_f32_e32 v119, 1.0, v158
	v_add_f32_e32 v149, 1.0, v114
	v_add_f32_e32 v160, 1.0, v115
	v_rcp_f32_e32 v114, v116
	v_rcp_f32_e32 v115, v117
	v_rcp_f32_e32 v116, v118
	v_rcp_f32_e32 v117, v119
	v_rcp_f32_e32 v118, v149
	v_rcp_f32_e32 v119, v160
	v_rcp_f32_e32 v112, v112
	v_rcp_f32_e32 v113, v113
	v_lshlrev_b64 v[158:159], 1, v[156:157]
	v_lshl_add_u64 v[160:161], s[10:11], 0, v[158:159]
	v_mul_f32_e32 v99, 0xbfb8aa3b, v99
	v_exp_f32_e32 v100, v100
	v_exp_f32_e32 v101, v101
	v_exp_f32_e32 v102, v102
	v_exp_f32_e32 v103, v103
	v_exp_f32_e32 v98, v98
	v_exp_f32_e32 v99, v99
	v_mul_f32_e32 v92, 0xbfb8aa3b, v92
	v_mul_f32_e32 v93, 0xbfb8aa3b, v93
	v_mul_f32_e32 v94, 0xbfb8aa3b, v94
	v_mul_f32_e32 v95, 0xbfb8aa3b, v95
	v_mul_f32_e32 v88, 0xbfb8aa3b, v88
	v_mul_f32_e32 v89, 0xbfb8aa3b, v89
	v_mul_f32_e32 v90, 0xbfb8aa3b, v90
	v_mul_f32_e32 v91, 0xbfb8aa3b, v91
	v_exp_f32_e32 v92, v92
	v_exp_f32_e32 v93, v93
	v_exp_f32_e32 v94, v94
	v_exp_f32_e32 v95, v95
	v_exp_f32_e32 v88, v88
	v_exp_f32_e32 v89, v89
	v_exp_f32_e32 v90, v90
	v_exp_f32_e32 v91, v91
	v_add_f32_e32 v92, 1.0, v92
	v_add_f32_e32 v93, 1.0, v93
	v_add_f32_e32 v94, 1.0, v94
	v_add_f32_e32 v95, 1.0, v95
	v_mul_f32_e32 v84, 0xbfb8aa3b, v84
	v_mul_f32_e32 v85, 0xbfb8aa3b, v85
	v_mul_f32_e32 v86, 0xbfb8aa3b, v86
	v_mul_f32_e32 v87, 0xbfb8aa3b, v87
	v_mul_f32_e32 v80, 0xbfb8aa3b, v80
	v_mul_f32_e32 v81, 0xbfb8aa3b, v81
	v_mul_f32_e32 v82, 0xbfb8aa3b, v82
	v_mul_f32_e32 v83, 0xbfb8aa3b, v83
	v_exp_f32_e32 v84, v84
	v_exp_f32_e32 v85, v85
	v_exp_f32_e32 v86, v86
	v_exp_f32_e32 v87, v87
	v_exp_f32_e32 v82, v82
	v_exp_f32_e32 v83, v83
	v_mul_f32_e32 v76, 0xbfb8aa3b, v76
	v_mul_f32_e32 v77, 0xbfb8aa3b, v77
	v_mul_f32_e32 v78, 0xbfb8aa3b, v78
	v_mul_f32_e32 v79, 0xbfb8aa3b, v79
	v_mul_f32_e32 v72, 0xbfb8aa3b, v72
	v_mul_f32_e32 v73, 0xbfb8aa3b, v73
	v_mul_f32_e32 v74, 0xbfb8aa3b, v74
	v_mul_f32_e32 v75, 0xbfb8aa3b, v75
	v_exp_f32_e32 v76, v76
	v_exp_f32_e32 v77, v77
	v_exp_f32_e32 v78, v78
	v_exp_f32_e32 v79, v79
	v_exp_f32_e32 v72, v72
	v_exp_f32_e32 v73, v73
	v_lshlrev_b32_e32 v168, 16, v120
	v_and_b32_e32 v169, 0xffff0000, v120
	v_lshlrev_b32_e32 v170, 16, v124
	v_and_b32_e32 v171, 0xffff0000, v124
	v_lshlrev_b32_e32 v120, 16, v121
	v_and_b32_e32 v121, 0xffff0000, v121
	v_lshlrev_b32_e32 v124, 16, v125
	v_and_b32_e32 v125, 0xffff0000, v125
	v_lshlrev_b32_e32 v162, 16, v122
	v_and_b32_e32 v163, 0xffff0000, v122
	v_lshlrev_b32_e32 v164, 16, v126
	v_and_b32_e32 v165, 0xffff0000, v126
	v_lshlrev_b32_e32 v122, 16, v123
	v_and_b32_e32 v123, 0xffff0000, v123
	v_lshlrev_b32_e32 v126, 16, v127
	v_and_b32_e32 v127, 0xffff0000, v127
	v_pk_fma_f32 v[116:117], v[116:117], v[168:169], v[170:171]
	v_pk_fma_f32 v[118:119], v[118:119], v[120:121], v[124:125]
	v_pk_fma_f32 v[112:113], v[112:113], v[162:163], v[164:165]
	v_pk_fma_f32 v[114:115], v[114:115], v[122:123], v[126:127]
	global_store_dwordx4 v[166:167], v[116:119], off offset:512
	global_store_dwordx4 v[166:167], v[112:115], off offset:528
	s_nop 1
	s_waitcnt vmcnt(18)
	v_mov_b32_e32 v112, v196
	v_mov_b32_e32 v113, v197
	v_mov_b32_e32 v114, v198
	v_mov_b32_e32 v115, v199
	v_lshl_add_u64 v[116:117], s[8:9], 0, v[158:159]
	s_nop 1
	v_mov_b32_e32 v116, v200
	v_mov_b32_e32 v117, v201
	v_mov_b32_e32 v118, v202
	v_mov_b32_e32 v119, v203
	s_mov_b64 s[98:99], 0x90000
	v_lshl_add_u64 v[250:251], v[246:247], 0, s[98:99]
	global_load_dwordx4 v[196:199], v[250:251], off
	v_lshl_add_u64 v[252:253], v[248:249], 0, s[98:99]
	global_load_dwordx4 v[200:203], v[252:253], off
	v_add_f32_e32 v122, 1.0, v104
	v_add_f32_e32 v123, 1.0, v105
	v_add_f32_e32 v124, 1.0, v106
	v_add_f32_e32 v125, 1.0, v107
	v_rcp_f32_e32 v104, v108
	v_rcp_f32_e32 v105, v109
	v_rcp_f32_e32 v106, v110
	v_rcp_f32_e32 v107, v111
	v_rcp_f32_e32 v108, v122
	v_rcp_f32_e32 v109, v123
	v_rcp_f32_e32 v110, v124
	v_rcp_f32_e32 v111, v125
	v_lshl_add_u64 v[120:121], v[156:157], 2, s[4:5]
	v_or_b32_e32 v158, 0x100, v158
	v_lshl_add_u64 v[122:123], s[10:11], 0, v[158:159]
	v_exp_f32_e32 v74, v74
	v_exp_f32_e32 v75, v75
	v_add_f32_e32 v76, 1.0, v76
	v_add_f32_e32 v77, 1.0, v77
	v_add_f32_e32 v78, 1.0, v78
	v_add_f32_e32 v79, 1.0, v79
	v_mul_f32_e32 v68, 0xbfb8aa3b, v68
	v_mul_f32_e32 v69, 0xbfb8aa3b, v69
	v_mul_f32_e32 v70, 0xbfb8aa3b, v70
	v_mul_f32_e32 v71, 0xbfb8aa3b, v71
	v_mul_f32_e32 v64, 0xbfb8aa3b, v64
	v_mul_f32_e32 v65, 0xbfb8aa3b, v65
	v_mul_f32_e32 v66, 0xbfb8aa3b, v66
	v_mul_f32_e32 v67, 0xbfb8aa3b, v67
	v_exp_f32_e32 v68, v68
	v_exp_f32_e32 v69, v69
	v_exp_f32_e32 v70, v70
	v_exp_f32_e32 v71, v71
	v_exp_f32_e32 v64, v64
	v_exp_f32_e32 v65, v65
	v_exp_f32_e32 v66, v66
	v_exp_f32_e32 v67, v67
	v_add_f32_e32 v68, 1.0, v68
	v_add_f32_e32 v69, 1.0, v69
	v_add_f32_e32 v70, 1.0, v70
	v_add_f32_e32 v71, 1.0, v71
	v_mul_f32_e32 v60, 0xbfb8aa3b, v60
	v_mul_f32_e32 v61, 0xbfb8aa3b, v61
	v_mul_f32_e32 v62, 0xbfb8aa3b, v62
	v_mul_f32_e32 v63, 0xbfb8aa3b, v63
	v_mul_f32_e32 v56, 0xbfb8aa3b, v56
	v_mul_f32_e32 v57, 0xbfb8aa3b, v57
	v_mul_f32_e32 v58, 0xbfb8aa3b, v58
	v_mul_f32_e32 v59, 0xbfb8aa3b, v59
	v_exp_f32_e32 v60, v60
	v_exp_f32_e32 v61, v61
	v_exp_f32_e32 v62, v62
	v_exp_f32_e32 v63, v63
	v_exp_f32_e32 v56, v56
	v_exp_f32_e32 v57, v57
	v_exp_f32_e32 v58, v58
	v_exp_f32_e32 v59, v59
	v_add_f32_e32 v60, 1.0, v60
	v_add_f32_e32 v61, 1.0, v61
	v_add_f32_e32 v62, 1.0, v62
	v_add_f32_e32 v63, 1.0, v63
	v_mul_f32_e32 v52, 0xbfb8aa3b, v52
	v_mul_f32_e32 v53, 0xbfb8aa3b, v53
	v_mul_f32_e32 v54, 0xbfb8aa3b, v54
	v_mul_f32_e32 v55, 0xbfb8aa3b, v55
	v_mul_f32_e32 v48, 0xbfb8aa3b, v48
	v_mul_f32_e32 v49, 0xbfb8aa3b, v49
	v_mul_f32_e32 v50, 0xbfb8aa3b, v50
	v_mul_f32_e32 v51, 0xbfb8aa3b, v51
	v_exp_f32_e32 v52, v52
	v_exp_f32_e32 v53, v53
	v_exp_f32_e32 v54, v54
	v_exp_f32_e32 v55, v55
	v_exp_f32_e32 v48, v48
	v_exp_f32_e32 v49, v49
	v_exp_f32_e32 v50, v50
	v_exp_f32_e32 v51, v51
	v_lshlrev_b32_e32 v156, 16, v112
	v_and_b32_e32 v157, 0xffff0000, v112
	v_lshlrev_b32_e32 v160, 16, v116
	v_and_b32_e32 v161, 0xffff0000, v116
	v_lshlrev_b32_e32 v112, 16, v113
	v_and_b32_e32 v113, 0xffff0000, v113
	v_lshlrev_b32_e32 v116, 16, v117
	v_and_b32_e32 v117, 0xffff0000, v117
	v_lshlrev_b32_e32 v124, 16, v114
	v_and_b32_e32 v125, 0xffff0000, v114
	v_lshlrev_b32_e32 v126, 16, v118
	v_and_b32_e32 v127, 0xffff0000, v118
	v_lshlrev_b32_e32 v114, 16, v115
	v_and_b32_e32 v115, 0xffff0000, v115
	v_lshlrev_b32_e32 v118, 16, v119
	v_and_b32_e32 v119, 0xffff0000, v119
	v_pk_fma_f32 v[108:109], v[108:109], v[156:157], v[160:161]
	v_pk_fma_f32 v[110:111], v[110:111], v[112:113], v[116:117]
	v_pk_fma_f32 v[104:105], v[104:105], v[124:125], v[126:127]
	v_pk_fma_f32 v[106:107], v[106:107], v[114:115], v[118:119]
	global_store_dwordx4 v[120:121], v[108:111], off
	global_store_dwordx4 v[120:121], v[104:107], off offset:16
	s_nop 1
	s_waitcnt vmcnt(20)
	v_mov_b32_e32 v104, v204
	v_mov_b32_e32 v105, v205
	v_mov_b32_e32 v106, v206
	v_mov_b32_e32 v107, v207
	v_lshl_add_u64 v[108:109], s[8:9], 0, v[158:159]
	s_nop 1
	v_mov_b32_e32 v108, v208
	v_mov_b32_e32 v109, v209
	v_mov_b32_e32 v110, v210
	v_mov_b32_e32 v111, v211
	s_mov_b64 s[98:99], 0x90000
	v_lshl_add_u64 v[250:251], v[246:247], 0, s[98:99]
	global_load_dwordx4 v[204:207], v[250:251], off offset:256
	v_lshl_add_u64 v[252:253], v[248:249], 0, s[98:99]
	global_load_dwordx4 v[208:211], v[252:253], off offset:256
	v_exp_f32_e32 v114, v96
	v_exp_f32_e32 v115, v97
	v_or_b32_e32 v96, 32, v148
	v_ashrrev_i32_e32 v97, 31, v96
	v_lshlrev_b64 v[96:97], 11, v[96:97]
	v_lshl_add_u64 v[112:113], v[96:97], 0, v[146:147]
	v_add_f32_e32 v96, 1.0, v100
	v_add_f32_e32 v97, 1.0, v101
	v_add_f32_e32 v100, 1.0, v102
	v_add_f32_e32 v101, 1.0, v103
	v_add_f32_e32 v102, 1.0, v114
	v_add_f32_e32 v103, 1.0, v115
	v_add_f32_e32 v116, 1.0, v98
	v_add_f32_e32 v117, 1.0, v99
	v_rcp_f32_e32 v98, v100
	v_rcp_f32_e32 v99, v101
	v_rcp_f32_e32 v100, v102
	v_rcp_f32_e32 v101, v103
	v_rcp_f32_e32 v102, v116
	v_rcp_f32_e32 v103, v117
	v_rcp_f32_e32 v96, v96
	v_rcp_f32_e32 v97, v97
	v_lshlrev_b64 v[114:115], 1, v[112:113]
	v_lshl_add_u64 v[116:117], s[10:11], 0, v[114:115]
	v_add_f32_e32 v52, 1.0, v52
	v_add_f32_e32 v53, 1.0, v53
	v_add_f32_e32 v54, 1.0, v54
	v_add_f32_e32 v55, 1.0, v55
	v_mul_f32_e32 v44, 0xbfb8aa3b, v44
	v_mul_f32_e32 v45, 0xbfb8aa3b, v45
	v_mul_f32_e32 v46, 0xbfb8aa3b, v46
	v_mul_f32_e32 v47, 0xbfb8aa3b, v47
	v_mul_f32_e32 v40, 0xbfb8aa3b, v40
	v_mul_f32_e32 v41, 0xbfb8aa3b, v41
	v_mul_f32_e32 v42, 0xbfb8aa3b, v42
	v_mul_f32_e32 v43, 0xbfb8aa3b, v43
	v_exp_f32_e32 v44, v44
	v_exp_f32_e32 v45, v45
	v_exp_f32_e32 v46, v46
	v_exp_f32_e32 v47, v47
	v_exp_f32_e32 v40, v40
	v_exp_f32_e32 v41, v41
	v_exp_f32_e32 v42, v42
	v_exp_f32_e32 v43, v43
	v_add_f32_e32 v44, 1.0, v44
	v_add_f32_e32 v45, 1.0, v45
	v_add_f32_e32 v46, 1.0, v46
	v_add_f32_e32 v47, 1.0, v47
	v_mul_f32_e32 v36, 0xbfb8aa3b, v36
	v_mul_f32_e32 v37, 0xbfb8aa3b, v37
	v_mul_f32_e32 v38, 0xbfb8aa3b, v38
	v_mul_f32_e32 v39, 0xbfb8aa3b, v39
	v_mul_f32_e32 v32, 0xbfb8aa3b, v32
	v_mul_f32_e32 v33, 0xbfb8aa3b, v33
	v_mul_f32_e32 v34, 0xbfb8aa3b, v34
	v_mul_f32_e32 v35, 0xbfb8aa3b, v35
	v_exp_f32_e32 v36, v36
	v_exp_f32_e32 v37, v37
	v_exp_f32_e32 v38, v38
	v_exp_f32_e32 v39, v39
	v_exp_f32_e32 v32, v32
	v_exp_f32_e32 v33, v33
	v_exp_f32_e32 v34, v34
	v_exp_f32_e32 v35, v35
	v_add_f32_e32 v36, 1.0, v36
	v_add_f32_e32 v37, 1.0, v37
	v_add_f32_e32 v38, 1.0, v38
	v_add_f32_e32 v39, 1.0, v39
	v_mul_f32_e32 v28, 0xbfb8aa3b, v28
	v_mul_f32_e32 v29, 0xbfb8aa3b, v29
	v_mul_f32_e32 v30, 0xbfb8aa3b, v30
	v_mul_f32_e32 v31, 0xbfb8aa3b, v31
	v_mul_f32_e32 v24, 0xbfb8aa3b, v24
	v_mul_f32_e32 v25, 0xbfb8aa3b, v25
	v_mul_f32_e32 v26, 0xbfb8aa3b, v26
	v_mul_f32_e32 v27, 0xbfb8aa3b, v27
	v_exp_f32_e32 v28, v28
	v_lshlrev_b32_e32 v124, 16, v104
	v_and_b32_e32 v125, 0xffff0000, v104
	v_lshlrev_b32_e32 v126, 16, v108
	v_and_b32_e32 v127, 0xffff0000, v108
	v_lshlrev_b32_e32 v104, 16, v105
	v_and_b32_e32 v105, 0xffff0000, v105
	v_lshlrev_b32_e32 v108, 16, v109
	v_and_b32_e32 v109, 0xffff0000, v109
	v_lshlrev_b32_e32 v118, 16, v106
	v_and_b32_e32 v119, 0xffff0000, v106
	v_lshlrev_b32_e32 v122, 16, v110
	v_and_b32_e32 v123, 0xffff0000, v110
	v_lshlrev_b32_e32 v106, 16, v107
	v_and_b32_e32 v107, 0xffff0000, v107
	v_lshlrev_b32_e32 v110, 16, v111
	v_and_b32_e32 v111, 0xffff0000, v111
	v_pk_fma_f32 v[100:101], v[100:101], v[124:125], v[126:127]
	v_pk_fma_f32 v[102:103], v[102:103], v[104:105], v[108:109]
	v_pk_fma_f32 v[96:97], v[96:97], v[118:119], v[122:123]
	v_pk_fma_f32 v[98:99], v[98:99], v[106:107], v[110:111]
	global_store_dwordx4 v[120:121], v[100:103], off offset:512
	global_store_dwordx4 v[120:121], v[96:99], off offset:528
	s_nop 1
	s_waitcnt vmcnt(22)
	v_mov_b32_e32 v96, v214
	v_mov_b32_e32 v97, v215
	v_mov_b32_e32 v98, v216
	v_mov_b32_e32 v99, v217
	v_lshl_add_u64 v[100:101], s[8:9], 0, v[114:115]
	s_nop 1
	v_mov_b32_e32 v100, v218
	v_mov_b32_e32 v101, v219
	v_mov_b32_e32 v102, v220
	v_mov_b32_e32 v103, v221
	s_mov_b64 s[98:99], 0xa0000
	v_lshl_add_u64 v[250:251], v[246:247], 0, s[98:99]
	global_load_dwordx4 v[214:217], v[250:251], off
	v_lshl_add_u64 v[252:253], v[248:249], 0, s[98:99]
	global_load_dwordx4 v[218:221], v[252:253], off
	v_add_f32_e32 v106, 1.0, v88
	v_add_f32_e32 v107, 1.0, v89
	v_add_f32_e32 v108, 1.0, v90
	v_add_f32_e32 v109, 1.0, v91
	v_rcp_f32_e32 v88, v92
	v_rcp_f32_e32 v89, v93
	v_rcp_f32_e32 v90, v94
	v_rcp_f32_e32 v91, v95
	v_rcp_f32_e32 v92, v106
	v_rcp_f32_e32 v93, v107
	v_rcp_f32_e32 v94, v108
	v_rcp_f32_e32 v95, v109
	v_lshl_add_u64 v[104:105], v[112:113], 2, s[4:5]
	v_or_b32_e32 v114, 0x100, v114
	v_lshl_add_u64 v[106:107], s[10:11], 0, v[114:115]
	v_exp_f32_e32 v29, v29
	v_exp_f32_e32 v30, v30
	v_exp_f32_e32 v31, v31
	v_exp_f32_e32 v24, v24
	v_exp_f32_e32 v25, v25
	v_exp_f32_e32 v26, v26
	v_exp_f32_e32 v27, v27
	v_add_f32_e32 v28, 1.0, v28
	v_add_f32_e32 v29, 1.0, v29
	v_add_f32_e32 v30, 1.0, v30
	v_add_f32_e32 v31, 1.0, v31
	v_mul_f32_e32 v20, 0xbfb8aa3b, v20
	v_mul_f32_e32 v21, 0xbfb8aa3b, v21
	v_mul_f32_e32 v22, 0xbfb8aa3b, v22
	v_mul_f32_e32 v23, 0xbfb8aa3b, v23
	v_mul_f32_e32 v16, 0xbfb8aa3b, v16
	v_mul_f32_e32 v17, 0xbfb8aa3b, v17
	v_mul_f32_e32 v18, 0xbfb8aa3b, v18
	v_mul_f32_e32 v19, 0xbfb8aa3b, v19
	v_exp_f32_e32 v20, v20
	v_exp_f32_e32 v21, v21
	v_exp_f32_e32 v22, v22
	v_exp_f32_e32 v23, v23
	v_exp_f32_e32 v16, v16
	v_exp_f32_e32 v17, v17
	v_exp_f32_e32 v18, v18
	v_exp_f32_e32 v19, v19
	v_add_f32_e32 v20, 1.0, v20
	v_add_f32_e32 v21, 1.0, v21
	v_add_f32_e32 v22, 1.0, v22
	v_add_f32_e32 v23, 1.0, v23
	v_mul_f32_e32 v12, 0xbfb8aa3b, v12
	v_mul_f32_e32 v13, 0xbfb8aa3b, v13
	v_mul_f32_e32 v14, 0xbfb8aa3b, v14
	v_mul_f32_e32 v15, 0xbfb8aa3b, v15
	v_mul_f32_e32 v8, 0xbfb8aa3b, v8
	v_mul_f32_e32 v9, 0xbfb8aa3b, v9
	v_mul_f32_e32 v10, 0xbfb8aa3b, v10
	v_mul_f32_e32 v11, 0xbfb8aa3b, v11
	v_exp_f32_e32 v12, v12
	v_exp_f32_e32 v13, v13
	v_exp_f32_e32 v14, v14
	v_exp_f32_e32 v15, v15
	v_exp_f32_e32 v8, v8
	v_exp_f32_e32 v9, v9
	v_exp_f32_e32 v10, v10
	v_exp_f32_e32 v11, v11
	v_add_f32_e32 v12, 1.0, v12
	v_add_f32_e32 v13, 1.0, v13
	v_add_f32_e32 v14, 1.0, v14
	v_add_f32_e32 v15, 1.0, v15
	v_mul_f32_e32 v4, 0xbfb8aa3b, v4
	v_mul_f32_e32 v5, 0xbfb8aa3b, v5
	v_mul_f32_e32 v6, 0xbfb8aa3b, v6
	v_mul_f32_e32 v7, 0xbfb8aa3b, v7
	v_mul_f32_e32 v0, 0xbfb8aa3b, v0
	v_mul_f32_e32 v1, 0xbfb8aa3b, v1
	v_mul_f32_e32 v2, 0xbfb8aa3b, v2
	v_mul_f32_e32 v3, 0xbfb8aa3b, v3
	v_exp_f32_e32 v4, v4
	v_exp_f32_e32 v5, v5
	v_exp_f32_e32 v6, v6
	v_lshlrev_b32_e32 v112, 16, v96
	v_and_b32_e32 v113, 0xffff0000, v96
	v_lshlrev_b32_e32 v116, 16, v100
	v_and_b32_e32 v117, 0xffff0000, v100
	v_lshlrev_b32_e32 v96, 16, v97
	v_and_b32_e32 v97, 0xffff0000, v97
	v_lshlrev_b32_e32 v100, 16, v101
	v_and_b32_e32 v101, 0xffff0000, v101
	v_lshlrev_b32_e32 v108, 16, v98
	v_and_b32_e32 v109, 0xffff0000, v98
	v_lshlrev_b32_e32 v110, 16, v102
	v_and_b32_e32 v111, 0xffff0000, v102
	v_lshlrev_b32_e32 v98, 16, v99
	v_and_b32_e32 v99, 0xffff0000, v99
	v_lshlrev_b32_e32 v102, 16, v103
	v_and_b32_e32 v103, 0xffff0000, v103
	v_pk_fma_f32 v[92:93], v[92:93], v[112:113], v[116:117]
	v_pk_fma_f32 v[94:95], v[94:95], v[96:97], v[100:101]
	v_pk_fma_f32 v[88:89], v[88:89], v[108:109], v[110:111]
	v_pk_fma_f32 v[90:91], v[90:91], v[98:99], v[102:103]
	global_store_dwordx4 v[104:105], v[92:95], off
	global_store_dwordx4 v[104:105], v[88:91], off offset:16
	s_nop 1
	s_waitcnt vmcnt(24)
	v_mov_b32_e32 v88, v222
	v_mov_b32_e32 v89, v223
	v_mov_b32_e32 v90, v224
	v_mov_b32_e32 v91, v225
	v_lshl_add_u64 v[92:93], s[8:9], 0, v[114:115]
	s_nop 1
	v_mov_b32_e32 v92, v226
	v_mov_b32_e32 v93, v227
	v_mov_b32_e32 v94, v228
	v_mov_b32_e32 v95, v229
	s_mov_b64 s[98:99], 0xa0000
	v_lshl_add_u64 v[250:251], v[246:247], 0, s[98:99]
	global_load_dwordx4 v[222:225], v[250:251], off offset:256
	v_lshl_add_u64 v[252:253], v[248:249], 0, s[98:99]
	global_load_dwordx4 v[226:229], v[252:253], off offset:256
	v_exp_f32_e32 v98, v80
	v_exp_f32_e32 v99, v81
	v_or_b32_e32 v80, 48, v148
	v_ashrrev_i32_e32 v81, 31, v80
	v_lshlrev_b64 v[80:81], 11, v[80:81]
	v_lshl_add_u64 v[96:97], v[80:81], 0, v[146:147]
	v_add_f32_e32 v80, 1.0, v84
	v_add_f32_e32 v81, 1.0, v85
	v_add_f32_e32 v84, 1.0, v86
	v_add_f32_e32 v85, 1.0, v87
	v_add_f32_e32 v86, 1.0, v98
	v_add_f32_e32 v87, 1.0, v99
	v_add_f32_e32 v100, 1.0, v82
	v_add_f32_e32 v101, 1.0, v83
	v_rcp_f32_e32 v82, v84
	v_rcp_f32_e32 v83, v85
	v_rcp_f32_e32 v84, v86
	v_rcp_f32_e32 v85, v87
	v_rcp_f32_e32 v86, v100
	v_rcp_f32_e32 v87, v101
	v_rcp_f32_e32 v80, v80
	v_rcp_f32_e32 v81, v81
	v_lshlrev_b64 v[98:99], 1, v[96:97]
	v_lshl_add_u64 v[100:101], s[10:11], 0, v[98:99]
	v_exp_f32_e32 v7, v7
	v_exp_f32_e32 v0, v0
	v_exp_f32_e32 v1, v1
	v_exp_f32_e32 v2, v2
	v_exp_f32_e32 v3, v3
	v_add_f32_e32 v4, 1.0, v4
	v_add_f32_e32 v5, 1.0, v5
	v_add_f32_e32 v6, 1.0, v6
	v_add_f32_e32 v7, 1.0, v7
	v_lshlrev_b32_e32 v108, 16, v88
	v_and_b32_e32 v109, 0xffff0000, v88
	v_lshlrev_b32_e32 v110, 16, v92
	v_and_b32_e32 v111, 0xffff0000, v92
	v_lshlrev_b32_e32 v88, 16, v89
	v_and_b32_e32 v89, 0xffff0000, v89
	v_lshlrev_b32_e32 v92, 16, v93
	v_and_b32_e32 v93, 0xffff0000, v93
	v_lshlrev_b32_e32 v102, 16, v90
	v_and_b32_e32 v103, 0xffff0000, v90
	v_lshlrev_b32_e32 v106, 16, v94
	v_and_b32_e32 v107, 0xffff0000, v94
	v_lshlrev_b32_e32 v90, 16, v91
	v_and_b32_e32 v91, 0xffff0000, v91
	v_lshlrev_b32_e32 v94, 16, v95
	v_and_b32_e32 v95, 0xffff0000, v95
	v_pk_fma_f32 v[84:85], v[84:85], v[108:109], v[110:111]
	v_pk_fma_f32 v[86:87], v[86:87], v[88:89], v[92:93]
	v_pk_fma_f32 v[80:81], v[80:81], v[102:103], v[106:107]
	v_pk_fma_f32 v[82:83], v[82:83], v[90:91], v[94:95]
	global_store_dwordx4 v[104:105], v[84:87], off offset:512
	global_store_dwordx4 v[104:105], v[80:83], off offset:528
	s_nop 1
	s_waitcnt vmcnt(26)
	v_mov_b32_e32 v80, v230
	v_mov_b32_e32 v81, v231
	v_mov_b32_e32 v82, v232
	v_mov_b32_e32 v83, v233
	v_lshl_add_u64 v[84:85], s[8:9], 0, v[98:99]
	s_nop 1
	v_mov_b32_e32 v84, v234
	v_mov_b32_e32 v85, v235
	v_mov_b32_e32 v86, v236
	v_mov_b32_e32 v87, v237
	s_mov_b64 s[98:99], 0xb0000
	v_lshl_add_u64 v[250:251], v[246:247], 0, s[98:99]
	global_load_dwordx4 v[230:233], v[250:251], off
	v_lshl_add_u64 v[252:253], v[248:249], 0, s[98:99]
	global_load_dwordx4 v[234:237], v[252:253], off
	v_add_f32_e32 v90, 1.0, v72
	v_add_f32_e32 v91, 1.0, v73
	v_add_f32_e32 v92, 1.0, v74
	v_add_f32_e32 v93, 1.0, v75
	v_rcp_f32_e32 v72, v76
	v_rcp_f32_e32 v73, v77
	v_rcp_f32_e32 v74, v78
	v_rcp_f32_e32 v75, v79
	v_rcp_f32_e32 v76, v90
	v_rcp_f32_e32 v77, v91
	v_rcp_f32_e32 v78, v92
	v_rcp_f32_e32 v79, v93
	v_lshl_add_u64 v[88:89], v[96:97], 2, s[4:5]
	v_or_b32_e32 v98, 0x100, v98
	v_lshl_add_u64 v[90:91], s[10:11], 0, v[98:99]
	v_lshlrev_b32_e32 v96, 16, v80
	v_and_b32_e32 v97, 0xffff0000, v80
	v_lshlrev_b32_e32 v100, 16, v84
	v_and_b32_e32 v101, 0xffff0000, v84
	v_lshlrev_b32_e32 v80, 16, v81
	v_and_b32_e32 v81, 0xffff0000, v81
	v_lshlrev_b32_e32 v84, 16, v85
	v_and_b32_e32 v85, 0xffff0000, v85
	v_lshlrev_b32_e32 v92, 16, v82
	v_and_b32_e32 v93, 0xffff0000, v82
	v_lshlrev_b32_e32 v94, 16, v86
	v_and_b32_e32 v95, 0xffff0000, v86
	v_lshlrev_b32_e32 v82, 16, v83
	v_and_b32_e32 v83, 0xffff0000, v83
	v_lshlrev_b32_e32 v86, 16, v87
	v_and_b32_e32 v87, 0xffff0000, v87
	v_pk_fma_f32 v[76:77], v[76:77], v[96:97], v[100:101]
	v_pk_fma_f32 v[78:79], v[78:79], v[80:81], v[84:85]
	v_pk_fma_f32 v[72:73], v[72:73], v[92:93], v[94:95]
	v_pk_fma_f32 v[74:75], v[74:75], v[82:83], v[86:87]
	global_store_dwordx4 v[88:89], v[76:79], off
	global_store_dwordx4 v[88:89], v[72:75], off offset:16
	s_nop 1
	s_waitcnt vmcnt(28)
	v_mov_b32_e32 v72, v238
	v_mov_b32_e32 v73, v239
	v_mov_b32_e32 v74, v240
	v_mov_b32_e32 v75, v241
	v_lshl_add_u64 v[76:77], s[8:9], 0, v[98:99]
	s_nop 1
	v_mov_b32_e32 v76, v242
	v_mov_b32_e32 v77, v243
	v_mov_b32_e32 v78, v244
	v_mov_b32_e32 v79, v245
	s_mov_b64 s[98:99], 0xb0000
	v_lshl_add_u64 v[250:251], v[246:247], 0, s[98:99]
	global_load_dwordx4 v[238:241], v[250:251], off offset:256
	v_lshl_add_u64 v[252:253], v[248:249], 0, s[98:99]
	global_load_dwordx4 v[242:245], v[252:253], off offset:256
	v_add_f32_e32 v84, 1.0, v64
	v_add_f32_e32 v85, 1.0, v65
	v_add_f32_e32 v86, 1.0, v66
	v_add_f32_e32 v87, 1.0, v67
	v_rcp_f32_e32 v64, v68
	v_rcp_f32_e32 v65, v69
	v_rcp_f32_e32 v66, v70
	v_rcp_f32_e32 v67, v71
	v_rcp_f32_e32 v68, v84
	v_rcp_f32_e32 v69, v85
	v_rcp_f32_e32 v70, v86
	v_rcp_f32_e32 v71, v87
	v_lshl_add_u64 v[80:81], v[144:145], 0, s[18:19]
	v_lshlrev_b64 v[82:83], 1, v[80:81]
	v_lshl_add_u64 v[84:85], s[10:11], 0, v[82:83]
	v_lshlrev_b32_e32 v92, 16, v72
	v_and_b32_e32 v93, 0xffff0000, v72
	v_lshlrev_b32_e32 v94, 16, v76
	v_and_b32_e32 v95, 0xffff0000, v76
	v_lshlrev_b32_e32 v72, 16, v73
	v_and_b32_e32 v73, 0xffff0000, v73
	v_lshlrev_b32_e32 v76, 16, v77
	v_and_b32_e32 v77, 0xffff0000, v77
	v_lshlrev_b32_e32 v86, 16, v74
	v_and_b32_e32 v87, 0xffff0000, v74
	v_lshlrev_b32_e32 v90, 16, v78
	v_and_b32_e32 v91, 0xffff0000, v78
	v_lshlrev_b32_e32 v74, 16, v75
	v_and_b32_e32 v75, 0xffff0000, v75
	v_lshlrev_b32_e32 v78, 16, v79
	v_and_b32_e32 v79, 0xffff0000, v79
	v_pk_fma_f32 v[68:69], v[68:69], v[92:93], v[94:95]
	v_pk_fma_f32 v[70:71], v[70:71], v[72:73], v[76:77]
	v_pk_fma_f32 v[64:65], v[64:65], v[86:87], v[90:91]
	v_pk_fma_f32 v[66:67], v[66:67], v[74:75], v[78:79]
	global_store_dwordx4 v[88:89], v[68:71], off offset:512
	global_store_dwordx4 v[88:89], v[64:67], off offset:528
	s_nop 1
	s_waitcnt vmcnt(30)
	v_mov_b32_e32 v64, v180
	v_mov_b32_e32 v65, v181
	v_mov_b32_e32 v66, v182
	v_mov_b32_e32 v67, v183
	v_lshl_add_u64 v[68:69], s[8:9], 0, v[82:83]
	s_nop 1
	v_mov_b32_e32 v68, v184
	v_mov_b32_e32 v69, v185
	v_mov_b32_e32 v70, v186
	v_mov_b32_e32 v71, v187
	v_add_f32_e32 v74, 1.0, v56
	v_add_f32_e32 v75, 1.0, v57
	v_add_f32_e32 v76, 1.0, v58
	v_add_f32_e32 v77, 1.0, v59
	v_rcp_f32_e32 v56, v60
	v_rcp_f32_e32 v57, v61
	v_rcp_f32_e32 v58, v62
	v_rcp_f32_e32 v59, v63
	v_rcp_f32_e32 v60, v74
	v_rcp_f32_e32 v61, v75
	v_rcp_f32_e32 v62, v76
	v_rcp_f32_e32 v63, v77
	v_lshl_add_u64 v[72:73], v[80:81], 2, s[4:5]
	v_or_b32_e32 v82, 0x100, v82
	v_lshl_add_u64 v[74:75], s[10:11], 0, v[82:83]
	v_lshlrev_b32_e32 v80, 16, v64
	v_and_b32_e32 v81, 0xffff0000, v64
	v_lshlrev_b32_e32 v84, 16, v68
	v_and_b32_e32 v85, 0xffff0000, v68
	v_lshlrev_b32_e32 v64, 16, v65
	v_and_b32_e32 v65, 0xffff0000, v65
	v_lshlrev_b32_e32 v68, 16, v69
	v_and_b32_e32 v69, 0xffff0000, v69
	v_lshlrev_b32_e32 v76, 16, v66
	v_and_b32_e32 v77, 0xffff0000, v66
	v_lshlrev_b32_e32 v78, 16, v70
	v_and_b32_e32 v79, 0xffff0000, v70
	v_lshlrev_b32_e32 v66, 16, v67
	v_and_b32_e32 v67, 0xffff0000, v67
	v_lshlrev_b32_e32 v70, 16, v71
	v_and_b32_e32 v71, 0xffff0000, v71
	v_pk_fma_f32 v[60:61], v[60:61], v[80:81], v[84:85]
	v_pk_fma_f32 v[62:63], v[62:63], v[64:65], v[68:69]
	v_pk_fma_f32 v[56:57], v[56:57], v[76:77], v[78:79]
	v_pk_fma_f32 v[58:59], v[58:59], v[66:67], v[70:71]
	global_store_dwordx4 v[72:73], v[60:63], off
	global_store_dwordx4 v[72:73], v[56:59], off offset:16
	s_nop 1
	s_waitcnt vmcnt(28)
	v_mov_b32_e32 v56, v188
	v_mov_b32_e32 v57, v189
	v_mov_b32_e32 v58, v190
	v_mov_b32_e32 v59, v191
	v_lshl_add_u64 v[60:61], s[8:9], 0, v[82:83]
	s_nop 1
	v_mov_b32_e32 v60, v192
	v_mov_b32_e32 v61, v193
	v_mov_b32_e32 v62, v194
	v_mov_b32_e32 v63, v195
	v_add_f32_e32 v68, 1.0, v48
	v_add_f32_e32 v69, 1.0, v49
	v_add_f32_e32 v70, 1.0, v50
	v_add_f32_e32 v71, 1.0, v51
	v_rcp_f32_e32 v48, v52
	v_rcp_f32_e32 v49, v53
	v_rcp_f32_e32 v50, v54
	v_rcp_f32_e32 v51, v55
	v_rcp_f32_e32 v52, v68
	v_rcp_f32_e32 v53, v69
	v_rcp_f32_e32 v54, v70
	v_rcp_f32_e32 v55, v71
	v_lshl_add_u64 v[64:65], v[144:145], 0, s[20:21]
	v_lshlrev_b64 v[66:67], 1, v[64:65]
	v_lshl_add_u64 v[68:69], s[10:11], 0, v[66:67]
	v_lshlrev_b32_e32 v76, 16, v56
	v_and_b32_e32 v77, 0xffff0000, v56
	v_lshlrev_b32_e32 v78, 16, v60
	v_and_b32_e32 v79, 0xffff0000, v60
	v_lshlrev_b32_e32 v56, 16, v57
	v_and_b32_e32 v57, 0xffff0000, v57
	v_lshlrev_b32_e32 v60, 16, v61
	v_and_b32_e32 v61, 0xffff0000, v61
	v_lshlrev_b32_e32 v70, 16, v58
	v_and_b32_e32 v71, 0xffff0000, v58
	v_lshlrev_b32_e32 v74, 16, v62
	v_and_b32_e32 v75, 0xffff0000, v62
	v_lshlrev_b32_e32 v58, 16, v59
	v_and_b32_e32 v59, 0xffff0000, v59
	v_lshlrev_b32_e32 v62, 16, v63
	v_and_b32_e32 v63, 0xffff0000, v63
	v_pk_fma_f32 v[52:53], v[52:53], v[76:77], v[78:79]
	v_pk_fma_f32 v[54:55], v[54:55], v[56:57], v[60:61]
	v_pk_fma_f32 v[48:49], v[48:49], v[70:71], v[74:75]
	v_pk_fma_f32 v[50:51], v[50:51], v[58:59], v[62:63]
	global_store_dwordx4 v[72:73], v[52:55], off offset:512
	global_store_dwordx4 v[72:73], v[48:51], off offset:528
	s_nop 1
	s_waitcnt vmcnt(26)
	v_mov_b32_e32 v48, v196
	v_mov_b32_e32 v49, v197
	v_mov_b32_e32 v50, v198
	v_mov_b32_e32 v51, v199
	v_lshl_add_u64 v[52:53], s[8:9], 0, v[66:67]
	s_nop 1
	v_mov_b32_e32 v52, v200
	v_mov_b32_e32 v53, v201
	v_mov_b32_e32 v54, v202
	v_mov_b32_e32 v55, v203
	v_add_f32_e32 v58, 1.0, v40
	v_add_f32_e32 v59, 1.0, v41
	v_add_f32_e32 v60, 1.0, v42
	v_add_f32_e32 v61, 1.0, v43
	v_rcp_f32_e32 v40, v44
	v_rcp_f32_e32 v41, v45
	v_rcp_f32_e32 v42, v46
	v_rcp_f32_e32 v43, v47
	v_rcp_f32_e32 v44, v58
	v_rcp_f32_e32 v45, v59
	v_rcp_f32_e32 v46, v60
	v_rcp_f32_e32 v47, v61
	v_lshl_add_u64 v[56:57], v[64:65], 2, s[4:5]
	v_or_b32_e32 v66, 0x100, v66
	v_lshl_add_u64 v[58:59], s[10:11], 0, v[66:67]
	v_lshlrev_b32_e32 v64, 16, v48
	v_and_b32_e32 v65, 0xffff0000, v48
	v_lshlrev_b32_e32 v68, 16, v52
	v_and_b32_e32 v69, 0xffff0000, v52
	v_lshlrev_b32_e32 v48, 16, v49
	v_and_b32_e32 v49, 0xffff0000, v49
	v_lshlrev_b32_e32 v52, 16, v53
	v_and_b32_e32 v53, 0xffff0000, v53
	v_lshlrev_b32_e32 v60, 16, v50
	v_and_b32_e32 v61, 0xffff0000, v50
	v_lshlrev_b32_e32 v62, 16, v54
	v_and_b32_e32 v63, 0xffff0000, v54
	v_lshlrev_b32_e32 v50, 16, v51
	v_and_b32_e32 v51, 0xffff0000, v51
	v_lshlrev_b32_e32 v54, 16, v55
	v_and_b32_e32 v55, 0xffff0000, v55
	v_pk_fma_f32 v[44:45], v[44:45], v[64:65], v[68:69]
	v_pk_fma_f32 v[46:47], v[46:47], v[48:49], v[52:53]
	v_pk_fma_f32 v[40:41], v[40:41], v[60:61], v[62:63]
	v_pk_fma_f32 v[42:43], v[42:43], v[50:51], v[54:55]
	global_store_dwordx4 v[56:57], v[44:47], off
	global_store_dwordx4 v[56:57], v[40:43], off offset:16
	s_nop 1
	s_waitcnt vmcnt(24)
	v_mov_b32_e32 v40, v204
	v_mov_b32_e32 v41, v205
	v_mov_b32_e32 v42, v206
	v_mov_b32_e32 v43, v207
	v_lshl_add_u64 v[44:45], s[8:9], 0, v[66:67]
	s_nop 1
	v_mov_b32_e32 v44, v208
	v_mov_b32_e32 v45, v209
	v_mov_b32_e32 v46, v210
	v_mov_b32_e32 v47, v211
	v_add_f32_e32 v52, 1.0, v32
	v_add_f32_e32 v53, 1.0, v33
	v_add_f32_e32 v54, 1.0, v34
	v_add_f32_e32 v55, 1.0, v35
	v_rcp_f32_e32 v32, v36
	v_rcp_f32_e32 v33, v37
	v_rcp_f32_e32 v34, v38
	v_rcp_f32_e32 v35, v39
	v_rcp_f32_e32 v36, v52
	v_rcp_f32_e32 v37, v53
	v_rcp_f32_e32 v38, v54
	v_rcp_f32_e32 v39, v55
	v_lshl_add_u64 v[48:49], v[144:145], 0, s[22:23]
	v_lshlrev_b64 v[50:51], 1, v[48:49]
	v_lshl_add_u64 v[52:53], s[10:11], 0, v[50:51]
	v_lshlrev_b32_e32 v60, 16, v40
	v_and_b32_e32 v61, 0xffff0000, v40
	v_lshlrev_b32_e32 v62, 16, v44
	v_and_b32_e32 v63, 0xffff0000, v44
	v_lshlrev_b32_e32 v40, 16, v41
	v_and_b32_e32 v41, 0xffff0000, v41
	v_lshlrev_b32_e32 v44, 16, v45
	v_and_b32_e32 v45, 0xffff0000, v45
	v_lshlrev_b32_e32 v54, 16, v42
	v_and_b32_e32 v55, 0xffff0000, v42
	v_lshlrev_b32_e32 v58, 16, v46
	v_and_b32_e32 v59, 0xffff0000, v46
	v_lshlrev_b32_e32 v42, 16, v43
	v_and_b32_e32 v43, 0xffff0000, v43
	v_lshlrev_b32_e32 v46, 16, v47
	v_and_b32_e32 v47, 0xffff0000, v47
	v_pk_fma_f32 v[36:37], v[36:37], v[60:61], v[62:63]
	v_pk_fma_f32 v[38:39], v[38:39], v[40:41], v[44:45]
	v_pk_fma_f32 v[32:33], v[32:33], v[54:55], v[58:59]
	v_pk_fma_f32 v[34:35], v[34:35], v[42:43], v[46:47]
	global_store_dwordx4 v[56:57], v[36:39], off offset:512
	global_store_dwordx4 v[56:57], v[32:35], off offset:528
	s_nop 1
	s_waitcnt vmcnt(22)
	v_mov_b32_e32 v32, v214
	v_mov_b32_e32 v33, v215
	v_mov_b32_e32 v34, v216
	v_mov_b32_e32 v35, v217
	v_lshl_add_u64 v[36:37], s[8:9], 0, v[50:51]
	s_nop 1
	v_mov_b32_e32 v36, v218
	v_mov_b32_e32 v37, v219
	v_mov_b32_e32 v38, v220
	v_mov_b32_e32 v39, v221
	v_add_f32_e32 v42, 1.0, v24
	v_add_f32_e32 v43, 1.0, v25
	v_add_f32_e32 v44, 1.0, v26
	v_add_f32_e32 v45, 1.0, v27
	v_rcp_f32_e32 v24, v28
	v_rcp_f32_e32 v25, v29
	v_rcp_f32_e32 v26, v30
	v_rcp_f32_e32 v27, v31
	v_rcp_f32_e32 v28, v42
	v_rcp_f32_e32 v29, v43
	v_rcp_f32_e32 v30, v44
	v_rcp_f32_e32 v31, v45
	v_lshl_add_u64 v[40:41], v[48:49], 2, s[4:5]
	v_or_b32_e32 v50, 0x100, v50
	v_lshl_add_u64 v[42:43], s[10:11], 0, v[50:51]
	v_lshlrev_b32_e32 v48, 16, v32
	v_and_b32_e32 v49, 0xffff0000, v32
	v_lshlrev_b32_e32 v52, 16, v36
	v_and_b32_e32 v53, 0xffff0000, v36
	v_lshlrev_b32_e32 v32, 16, v33
	v_and_b32_e32 v33, 0xffff0000, v33
	v_lshlrev_b32_e32 v36, 16, v37
	v_and_b32_e32 v37, 0xffff0000, v37
	v_lshlrev_b32_e32 v44, 16, v34
	v_and_b32_e32 v45, 0xffff0000, v34
	v_lshlrev_b32_e32 v46, 16, v38
	v_and_b32_e32 v47, 0xffff0000, v38
	v_lshlrev_b32_e32 v34, 16, v35
	v_and_b32_e32 v35, 0xffff0000, v35
	v_lshlrev_b32_e32 v38, 16, v39
	v_and_b32_e32 v39, 0xffff0000, v39
	v_pk_fma_f32 v[28:29], v[28:29], v[48:49], v[52:53]
	v_pk_fma_f32 v[30:31], v[30:31], v[32:33], v[36:37]
	v_pk_fma_f32 v[24:25], v[24:25], v[44:45], v[46:47]
	v_pk_fma_f32 v[26:27], v[26:27], v[34:35], v[38:39]
	global_store_dwordx4 v[40:41], v[28:31], off
	global_store_dwordx4 v[40:41], v[24:27], off offset:16
	s_nop 1
	s_waitcnt vmcnt(20)
	v_mov_b32_e32 v24, v222
	v_mov_b32_e32 v25, v223
	v_mov_b32_e32 v26, v224
	v_mov_b32_e32 v27, v225
	v_lshl_add_u64 v[28:29], s[8:9], 0, v[50:51]
	s_nop 1
	v_mov_b32_e32 v28, v226
	v_mov_b32_e32 v29, v227
	v_mov_b32_e32 v30, v228
	v_mov_b32_e32 v31, v229
	v_add_f32_e32 v36, 1.0, v16
	v_add_f32_e32 v37, 1.0, v17
	v_add_f32_e32 v38, 1.0, v18
	v_add_f32_e32 v39, 1.0, v19
	v_rcp_f32_e32 v16, v20
	v_rcp_f32_e32 v17, v21
	v_rcp_f32_e32 v18, v22
	v_rcp_f32_e32 v19, v23
	v_rcp_f32_e32 v20, v36
	v_rcp_f32_e32 v21, v37
	v_rcp_f32_e32 v22, v38
	v_rcp_f32_e32 v23, v39
	v_lshl_add_u64 v[32:33], v[144:145], 0, s[24:25]
	v_lshlrev_b64 v[34:35], 1, v[32:33]
	v_lshl_add_u64 v[36:37], s[10:11], 0, v[34:35]
	v_lshlrev_b32_e32 v44, 16, v24
	v_and_b32_e32 v45, 0xffff0000, v24
	v_lshlrev_b32_e32 v46, 16, v28
	v_and_b32_e32 v47, 0xffff0000, v28
	v_lshlrev_b32_e32 v24, 16, v25
	v_and_b32_e32 v25, 0xffff0000, v25
	v_lshlrev_b32_e32 v28, 16, v29
	v_and_b32_e32 v29, 0xffff0000, v29
	v_lshlrev_b32_e32 v38, 16, v26
	v_and_b32_e32 v39, 0xffff0000, v26
	v_lshlrev_b32_e32 v42, 16, v30
	v_and_b32_e32 v43, 0xffff0000, v30
	v_lshlrev_b32_e32 v26, 16, v27
	v_and_b32_e32 v27, 0xffff0000, v27
	v_lshlrev_b32_e32 v30, 16, v31
	v_and_b32_e32 v31, 0xffff0000, v31
	v_pk_fma_f32 v[20:21], v[20:21], v[44:45], v[46:47]
	v_pk_fma_f32 v[22:23], v[22:23], v[24:25], v[28:29]
	v_pk_fma_f32 v[16:17], v[16:17], v[38:39], v[42:43]
	v_pk_fma_f32 v[18:19], v[18:19], v[26:27], v[30:31]
	global_store_dwordx4 v[40:41], v[20:23], off offset:512
	global_store_dwordx4 v[40:41], v[16:19], off offset:528
	s_nop 1
	s_waitcnt vmcnt(18)
	v_mov_b32_e32 v16, v230
	v_mov_b32_e32 v17, v231
	v_mov_b32_e32 v18, v232
	v_mov_b32_e32 v19, v233
	v_lshl_add_u64 v[20:21], s[8:9], 0, v[34:35]
	s_nop 1
	v_mov_b32_e32 v20, v234
	v_mov_b32_e32 v21, v235
	v_mov_b32_e32 v22, v236
	v_mov_b32_e32 v23, v237
	v_add_f32_e32 v26, 1.0, v8
	v_add_f32_e32 v27, 1.0, v9
	v_add_f32_e32 v28, 1.0, v10
	v_add_f32_e32 v29, 1.0, v11
	v_rcp_f32_e32 v8, v12
	v_rcp_f32_e32 v9, v13
	v_rcp_f32_e32 v10, v14
	v_rcp_f32_e32 v11, v15
	v_rcp_f32_e32 v12, v26
	v_rcp_f32_e32 v13, v27
	v_rcp_f32_e32 v14, v28
	v_rcp_f32_e32 v15, v29
	v_lshl_add_u64 v[24:25], v[32:33], 2, s[4:5]
	v_or_b32_e32 v34, 0x100, v34
	v_lshl_add_u64 v[26:27], s[10:11], 0, v[34:35]
	v_lshlrev_b32_e32 v32, 16, v16
	v_and_b32_e32 v33, 0xffff0000, v16
	v_lshlrev_b32_e32 v36, 16, v20
	v_and_b32_e32 v37, 0xffff0000, v20
	v_lshlrev_b32_e32 v16, 16, v17
	v_and_b32_e32 v17, 0xffff0000, v17
	v_lshlrev_b32_e32 v20, 16, v21
	v_and_b32_e32 v21, 0xffff0000, v21
	v_lshlrev_b32_e32 v28, 16, v18
	v_and_b32_e32 v29, 0xffff0000, v18
	v_lshlrev_b32_e32 v30, 16, v22
	v_and_b32_e32 v31, 0xffff0000, v22
	v_lshlrev_b32_e32 v18, 16, v19
	v_and_b32_e32 v19, 0xffff0000, v19
	v_lshlrev_b32_e32 v22, 16, v23
	v_and_b32_e32 v23, 0xffff0000, v23
	v_pk_fma_f32 v[12:13], v[12:13], v[32:33], v[36:37]
	v_pk_fma_f32 v[14:15], v[14:15], v[16:17], v[20:21]
	v_pk_fma_f32 v[8:9], v[8:9], v[28:29], v[30:31]
	v_pk_fma_f32 v[10:11], v[10:11], v[18:19], v[22:23]
	global_store_dwordx4 v[24:25], v[12:15], off
	global_store_dwordx4 v[24:25], v[8:11], off offset:16
	s_nop 1
	s_waitcnt vmcnt(16)
	v_mov_b32_e32 v8, v238
	v_mov_b32_e32 v9, v239
	v_mov_b32_e32 v10, v240
	v_mov_b32_e32 v11, v241
	v_lshl_add_u64 v[12:13], s[8:9], 0, v[34:35]
	s_nop 1
	v_mov_b32_e32 v12, v242
	v_mov_b32_e32 v13, v243
	v_mov_b32_e32 v14, v244
	v_mov_b32_e32 v15, v245
	v_add_f32_e32 v16, 1.0, v0
	v_add_f32_e32 v17, 1.0, v1
	v_add_f32_e32 v18, 1.0, v2
	v_add_f32_e32 v19, 1.0, v3
	v_rcp_f32_e32 v0, v4
	v_rcp_f32_e32 v1, v5
	v_rcp_f32_e32 v2, v6
	v_rcp_f32_e32 v3, v7
	v_rcp_f32_e32 v4, v16
	v_rcp_f32_e32 v5, v17
	v_rcp_f32_e32 v6, v18
	v_rcp_f32_e32 v7, v19
	v_lshlrev_b32_e32 v20, 16, v8
	v_and_b32_e32 v21, 0xffff0000, v8
	v_lshlrev_b32_e32 v22, 16, v12
	v_and_b32_e32 v23, 0xffff0000, v12
	v_lshlrev_b32_e32 v8, 16, v9
	v_and_b32_e32 v9, 0xffff0000, v9
	v_lshlrev_b32_e32 v12, 16, v13
	v_and_b32_e32 v13, 0xffff0000, v13
	v_lshlrev_b32_e32 v16, 16, v10
	v_and_b32_e32 v17, 0xffff0000, v10
	v_lshlrev_b32_e32 v18, 16, v14
	v_and_b32_e32 v19, 0xffff0000, v14
	v_lshlrev_b32_e32 v10, 16, v11
	v_and_b32_e32 v11, 0xffff0000, v11
	v_lshlrev_b32_e32 v14, 16, v15
	v_and_b32_e32 v15, 0xffff0000, v15
	v_pk_fma_f32 v[4:5], v[4:5], v[20:21], v[22:23]
	v_pk_fma_f32 v[6:7], v[6:7], v[8:9], v[12:13]
	v_pk_fma_f32 v[0:1], v[0:1], v[16:17], v[18:19]
	v_pk_fma_f32 v[2:3], v[2:3], v[10:11], v[14:15]
	global_store_dwordx4 v[24:25], v[4:7], off offset:512
	global_store_dwordx4 v[24:25], v[0:3], off offset:528
	s_andn2_b64 vcc, exec, s[0:1]
	s_mov_b64 s[0:1], -1
	s_cbranch_vccnz .LBB0_2172
